# FFN1 int8 epilogue: preload the 8 per-row frow scales once instead of a serialized load + vmcnt(0) drain per row (4 layers)
# speedup vs baseline: 1.0028x; 1.0028x over previous
.LBB0_1091:
	s_lshl_b32 s30, s36, 8
	s_add_i32 s34, s30, s62
	s_lshl_b32 s30, s37, 8
	s_or_b32 s35, s30, s63
	s_lshr_b32 s30, s36, 4
	s_add_i32 s30, s30, -1
	v_or_b32_e32 v2, s35, v186
	s_cmp_gt_i32 s36, 31
	s_cselect_b32 s30, s30, 0
	v_ashrrev_i32_e32 v3, 31, v2
	v_or_b32_e32 v168, s34, v187
	v_lshlrev_b64 v[10:11], 2, v[2:3]
	v_ashrrev_i32_e32 v169, 31, v168
	s_ashr_i32 s31, s30, 31
	v_lshl_add_u64 v[12:13], s[20:21], 0, v[10:11]
	v_lshl_add_u64 v[100:101], v[168:169], 2, s[16:17]
	s_lshl_b64 s[30:31], s[30:31], 15
	global_load_dwordx4 v[2:5], v[12:13], off offset:16
	global_load_dwordx4 v[6:9], v[12:13], off
	global_load_dword v190, v[100:101], off
	global_load_dword v240, v[100:101], off offset:64
	global_load_dword v241, v[100:101], off offset:128
	global_load_dword v242, v[100:101], off offset:192
	global_load_dword v243, v[100:101], off offset:512
	global_load_dword v244, v[100:101], off offset:576
	global_load_dword v245, v[100:101], off offset:640
	global_load_dword v246, v[100:101], off offset:704
	s_add_u32 s30, s57, s30
	global_load_dwordx4 v[14:17], v[12:13], off offset:528
	global_load_dwordx4 v[30:33], v[12:13], off offset:512
	s_addc_u32 s31, s58, s31
	v_lshl_add_u64 v[10:11], s[30:31], 0, v[10:11]
	global_load_dwordx4 v[26:29], v[10:11], off
	global_load_dwordx4 v[22:25], v[10:11], off offset:16
	global_load_dwordx4 v[18:21], v[10:11], off offset:512
	s_nop 0
	global_load_dwordx4 v[10:13], v[10:11], off offset:528
	s_ashr_i32 s34, s34, 8
	v_bitop3_b32 v90, s35, 56, v186 bitop3:0xc8
	s_ashr_i32 s30, s35, 6
	s_ashr_i32 s35, s34, 31
	s_ashr_i32 s31, s30, 31
	s_lshl_b64 s[38:39], s[34:35], 7
	s_add_u32 s34, s38, s30
	s_addc_u32 s35, s39, s31
	s_lshl_b64 s[34:35], s[34:35], 15
	s_add_u32 s36, s12, s34
	s_addc_u32 s37, s13, s35
	s_or_b32 s34, s30, 2
	s_ashr_i32 s35, s34, 31
	s_add_u32 s38, s38, s34
	v_lshlrev_b32_e32 v169, 7, v168
	s_addc_u32 s39, s39, s35
	v_and_b32_e32 v138, 0x6780, v169
	s_lshl_b64 s[38:39], s[38:39], 15
	v_mov_b32_e32 v91, v139
	v_lshlrev_b32_e32 v90, 1, v90
	v_lshl_add_u64 v[192:193], s[36:37], 0, v[138:139]
	s_add_u32 s38, s12, s38
	v_lshl_add_u64 v[192:193], v[192:193], 0, v[90:91]
	s_addc_u32 s39, s13, s39
	s_and_b64 vcc, exec, s[0:1]
	s_mov_b64 s[0:1], -1
	s_waitcnt vmcnt(0)
	v_pk_mul_f32 v[194:195], v[6:7], v[190:191] op_sel_hi:[1,0]
	v_pk_mul_f32 v[196:197], v[8:9], v[190:191] op_sel_hi:[1,0]
	v_pk_mul_f32 v[198:199], v[2:3], v[190:191] op_sel_hi:[1,0]
	v_pk_mul_f32 v[204:205], v[32:33], v[190:191] op_sel_hi:[1,0]
	v_pk_fma_f32 v[170:171], v[196:197], v[170:171], v[28:29]
	v_pk_fma_f32 v[172:173], v[194:195], v[172:173], v[26:27]
	v_pk_mul_f32 v[200:201], v[4:5], v[190:191] op_sel_hi:[1,0]
	v_pk_mul_f32 v[202:203], v[30:31], v[190:191] op_sel_hi:[1,0]
	v_pk_mul_f32 v[206:207], v[14:15], v[190:191] op_sel_hi:[1,0]
	v_pk_mul_f32 v[190:191], v[16:17], v[190:191] op_sel_hi:[1,0]
	v_pk_fma_f32 v[174:175], v[198:199], v[174:175], v[22:23]
	v_pk_fma_f32 v[182:183], v[204:205], v[182:183], v[20:21]
	v_max_f32_e32 v173, 0, v173
	v_max_f32_e32 v172, 0, v172
	v_max_f32_e32 v171, 0, v171
	v_max_f32_e32 v170, 0, v170
	v_pk_fma_f32 v[176:177], v[200:201], v[176:177], v[24:25]
	v_pk_fma_f32 v[180:181], v[202:203], v[180:181], v[18:19]
	v_pk_fma_f32 v[184:185], v[190:191], v[184:185], v[12:13]
	v_max_f32_e32 v175, 0, v175
	v_max_f32_e32 v174, 0, v174
	v_max_f32_e32 v183, 0, v183
	v_max_f32_e32 v182, 0, v182
	v_pk_mul_f32 v[190:191], v[170:171], v[170:171]
	v_pk_mul_f32 v[170:171], v[172:173], v[172:173]
	v_max_f32_e32 v177, 0, v177
	v_max_f32_e32 v176, 0, v176
	v_max_f32_e32 v181, 0, v181
	v_max_f32_e32 v180, 0, v180
	v_pk_mul_f32 v[172:173], v[174:175], v[174:175]
	v_pk_mul_f32 v[174:175], v[182:183], v[182:183]
	v_cvt_pk_bf16_f32 v170, v170, v171
	v_cvt_pk_bf16_f32 v171, v190, v191
	v_pk_fma_f32 v[178:179], v[206:207], v[178:179], v[10:11]
	v_pk_mul_f32 v[176:177], v[176:177], v[176:177]
	v_pk_mul_f32 v[180:181], v[180:181], v[180:181]
	v_cvt_pk_bf16_f32 v172, v172, v173
	v_cvt_pk_bf16_f32 v173, v176, v177
	global_store_dwordx4 v[192:193], v[170:173], off
	v_max_f32_e32 v179, 0, v179
	v_max_f32_e32 v178, 0, v178
	v_cvt_pk_bf16_f32 v170, v180, v181
	v_cvt_pk_bf16_f32 v171, v174, v175
	v_lshl_add_u64 v[174:175], s[38:39], 0, v[138:139]
	v_max_f32_e32 v185, 0, v185
	v_max_f32_e32 v184, 0, v184
	v_lshl_add_u64 v[174:175], v[174:175], 0, v[90:91]
	v_pk_mul_f32 v[182:183], v[184:185], v[184:185]
	v_pk_mul_f32 v[178:179], v[178:179], v[178:179]
	s_nop 0
	v_cvt_pk_bf16_f32 v172, v178, v179
	v_cvt_pk_bf16_f32 v173, v182, v183
	global_store_dwordx4 v[174:175], v[170:173], off
	v_or_b32_e32 v174, 32, v168
	v_ashrrev_i32_e32 v175, 31, v174
	v_or_b32_e32 v170, 16, v168
	v_ashrrev_i32_e32 v171, 31, v170
	v_lshl_add_u64 v[172:173], v[170:171], 2, s[16:17]
	s_nop 1
	v_mov_b32_e32 v172, v240
	v_lshlrev_b32_e32 v138, 7, v170
	v_and_b32_e32 v138, 0x6f80, v138
	v_lshl_add_u64 v[176:177], s[36:37], 0, v[138:139]
	v_lshl_add_u64 v[178:179], s[38:39], 0, v[138:139]
	v_lshl_add_u64 v[176:177], v[176:177], 0, v[90:91]
	v_lshl_add_u64 v[178:179], v[178:179], 0, v[90:91]
	v_lshl_add_u64 v[170:171], v[174:175], 2, s[16:17]
	v_lshlrev_b32_e32 v138, 7, v174
	v_and_b32_e32 v138, 0x7780, v138
	s_nop 0
	v_pk_mul_f32 v[180:181], v[6:7], v[172:173] op_sel_hi:[1,0]
	v_pk_mul_f32 v[182:183], v[8:9], v[172:173] op_sel_hi:[1,0]
	v_pk_mul_f32 v[184:185], v[2:3], v[172:173] op_sel_hi:[1,0]
	v_pk_mul_f32 v[190:191], v[4:5], v[172:173] op_sel_hi:[1,0]
	v_pk_fma_f32 v[154:155], v[182:183], v[154:155], v[28:29]
	v_pk_fma_f32 v[152:153], v[180:181], v[152:153], v[26:27]
	v_pk_mul_f32 v[192:193], v[30:31], v[172:173] op_sel_hi:[1,0]
	v_pk_mul_f32 v[194:195], v[32:33], v[172:173] op_sel_hi:[1,0]
	v_pk_mul_f32 v[196:197], v[14:15], v[172:173] op_sel_hi:[1,0]
	v_pk_mul_f32 v[172:173], v[16:17], v[172:173] op_sel_hi:[1,0]
	v_pk_fma_f32 v[158:159], v[190:191], v[158:159], v[24:25]
	v_pk_fma_f32 v[156:157], v[184:185], v[156:157], v[22:23]
	v_max_f32_e32 v153, 0, v153
	v_max_f32_e32 v152, 0, v152
	v_max_f32_e32 v155, 0, v155
	v_max_f32_e32 v154, 0, v154
	v_pk_fma_f32 v[162:163], v[194:195], v[162:163], v[20:21]
	v_pk_fma_f32 v[160:161], v[192:193], v[160:161], v[18:19]
	v_pk_fma_f32 v[166:167], v[172:173], v[166:167], v[12:13]
	v_pk_fma_f32 v[164:165], v[196:197], v[164:165], v[10:11]
	v_max_f32_e32 v157, 0, v157
	v_max_f32_e32 v156, 0, v156
	v_max_f32_e32 v159, 0, v159
	v_max_f32_e32 v158, 0, v158
	v_pk_mul_f32 v[154:155], v[154:155], v[154:155]
	v_pk_mul_f32 v[152:153], v[152:153], v[152:153]
	v_max_f32_e32 v161, 0, v161
	v_max_f32_e32 v160, 0, v160
	v_max_f32_e32 v163, 0, v163
	v_max_f32_e32 v162, 0, v162
	v_max_f32_e32 v165, 0, v165
	v_max_f32_e32 v164, 0, v164
	v_max_f32_e32 v167, 0, v167
	v_max_f32_e32 v166, 0, v166
	v_pk_mul_f32 v[158:159], v[158:159], v[158:159]
	v_pk_mul_f32 v[156:157], v[156:157], v[156:157]
	v_cvt_pk_bf16_f32 v152, v152, v153
	v_cvt_pk_bf16_f32 v153, v154, v155
	v_pk_mul_f32 v[162:163], v[162:163], v[162:163]
	v_cvt_pk_bf16_f32 v154, v156, v157
	v_cvt_pk_bf16_f32 v155, v158, v159
	v_pk_mul_f32 v[160:161], v[160:161], v[160:161]
	v_pk_mul_f32 v[166:167], v[166:167], v[166:167]
	v_pk_mul_f32 v[164:165], v[164:165], v[164:165]
	global_store_dwordx4 v[176:177], v[152:155], off
	v_lshl_add_u64 v[158:159], s[36:37], 0, v[138:139]
	v_lshl_add_u64 v[158:159], v[158:159], 0, v[90:91]
	v_cvt_pk_bf16_f32 v152, v160, v161
	v_cvt_pk_bf16_f32 v153, v162, v163
	v_cvt_pk_bf16_f32 v154, v164, v165
	v_cvt_pk_bf16_f32 v155, v166, v167
	global_store_dwordx4 v[178:179], v[152:155], off
	s_nop 1
	v_mov_b32_e32 v152, v241
	v_lshl_add_u64 v[160:161], s[38:39], 0, v[138:139]
	v_or_b32_e32 v154, 48, v168
	v_ashrrev_i32_e32 v155, 31, v154
	v_lshl_add_u64 v[160:161], v[160:161], 0, v[90:91]
	v_lshl_add_u64 v[156:157], v[154:155], 2, s[16:17]
	s_nop 0
	v_pk_mul_f32 v[162:163], v[6:7], v[152:153] op_sel_hi:[1,0]
	v_pk_mul_f32 v[164:165], v[8:9], v[152:153] op_sel_hi:[1,0]
	v_pk_mul_f32 v[166:167], v[2:3], v[152:153] op_sel_hi:[1,0]
	v_pk_mul_f32 v[170:171], v[4:5], v[152:153] op_sel_hi:[1,0]
	v_pk_fma_f32 v[120:121], v[164:165], v[120:121], v[28:29]
	v_pk_fma_f32 v[118:119], v[162:163], v[118:119], v[26:27]
	v_pk_mul_f32 v[172:173], v[30:31], v[152:153] op_sel_hi:[1,0]
	v_pk_mul_f32 v[174:175], v[32:33], v[152:153] op_sel_hi:[1,0]
	v_pk_mul_f32 v[176:177], v[14:15], v[152:153] op_sel_hi:[1,0]
	v_pk_mul_f32 v[152:153], v[16:17], v[152:153] op_sel_hi:[1,0]
	v_pk_fma_f32 v[124:125], v[170:171], v[124:125], v[24:25]
	v_pk_fma_f32 v[122:123], v[166:167], v[122:123], v[22:23]
	v_max_f32_e32 v119, 0, v119
	v_max_f32_e32 v118, 0, v118
	v_max_f32_e32 v121, 0, v121
	v_max_f32_e32 v120, 0, v120
	v_pk_fma_f32 v[128:129], v[174:175], v[128:129], v[20:21]
	v_pk_fma_f32 v[126:127], v[172:173], v[126:127], v[18:19]
	v_pk_fma_f32 v[150:151], v[152:153], v[150:151], v[12:13]
	v_pk_fma_f32 v[148:149], v[176:177], v[148:149], v[10:11]
	v_max_f32_e32 v123, 0, v123
	v_max_f32_e32 v122, 0, v122
	v_max_f32_e32 v125, 0, v125
	v_max_f32_e32 v124, 0, v124
	v_pk_mul_f32 v[120:121], v[120:121], v[120:121]
	v_pk_mul_f32 v[118:119], v[118:119], v[118:119]
	v_max_f32_e32 v127, 0, v127
	v_max_f32_e32 v126, 0, v126
	v_max_f32_e32 v129, 0, v129
	v_max_f32_e32 v128, 0, v128
	v_max_f32_e32 v149, 0, v149
	v_max_f32_e32 v148, 0, v148
	v_max_f32_e32 v151, 0, v151
	v_max_f32_e32 v150, 0, v150
	v_pk_mul_f32 v[124:125], v[124:125], v[124:125]
	v_pk_mul_f32 v[122:123], v[122:123], v[122:123]
	v_cvt_pk_bf16_f32 v118, v118, v119
	v_cvt_pk_bf16_f32 v119, v120, v121
	v_pk_mul_f32 v[128:129], v[128:129], v[128:129]
	v_cvt_pk_bf16_f32 v120, v122, v123
	v_cvt_pk_bf16_f32 v121, v124, v125
	v_pk_mul_f32 v[126:127], v[126:127], v[126:127]
	v_pk_mul_f32 v[150:151], v[150:151], v[150:151]
	v_pk_mul_f32 v[148:149], v[148:149], v[148:149]
	global_store_dwordx4 v[158:159], v[118:121], off
	s_nop 1
	v_cvt_pk_bf16_f32 v118, v126, v127
	v_cvt_pk_bf16_f32 v119, v128, v129
	v_cvt_pk_bf16_f32 v120, v148, v149
	v_cvt_pk_bf16_f32 v121, v150, v151
	global_store_dwordx4 v[160:161], v[118:121], off
	s_nop 1
	v_mov_b32_e32 v118, v242
	s_nop 0
	v_lshlrev_b32_e32 v119, 7, v154
	v_and_b32_e32 v138, 0x7f80, v119
	v_lshl_add_u64 v[120:121], s[36:37], 0, v[138:139]
	v_lshl_add_u64 v[122:123], s[38:39], 0, v[138:139]
	v_lshl_add_u64 v[120:121], v[120:121], 0, v[90:91]
	v_lshl_add_u64 v[122:123], v[122:123], 0, v[90:91]
	s_nop 0
	v_pk_mul_f32 v[124:125], v[6:7], v[118:119] op_sel_hi:[1,0]
	v_pk_mul_f32 v[126:127], v[8:9], v[118:119] op_sel_hi:[1,0]
	v_pk_mul_f32 v[128:129], v[2:3], v[118:119] op_sel_hi:[1,0]
	v_pk_mul_f32 v[148:149], v[4:5], v[118:119] op_sel_hi:[1,0]
	v_pk_fma_f32 v[104:105], v[126:127], v[104:105], v[28:29]
	v_pk_fma_f32 v[102:103], v[124:125], v[102:103], v[26:27]
	v_pk_mul_f32 v[150:151], v[30:31], v[118:119] op_sel_hi:[1,0]
	v_pk_mul_f32 v[152:153], v[32:33], v[118:119] op_sel_hi:[1,0]
	v_pk_mul_f32 v[154:155], v[14:15], v[118:119] op_sel_hi:[1,0]
	v_pk_mul_f32 v[118:119], v[16:17], v[118:119] op_sel_hi:[1,0]
	v_pk_fma_f32 v[108:109], v[148:149], v[108:109], v[24:25]
	v_pk_fma_f32 v[106:107], v[128:129], v[106:107], v[22:23]
	v_max_f32_e32 v103, 0, v103
	v_max_f32_e32 v102, 0, v102
	v_max_f32_e32 v105, 0, v105
	v_max_f32_e32 v104, 0, v104
	v_pk_fma_f32 v[112:113], v[152:153], v[112:113], v[20:21]
	v_pk_fma_f32 v[110:111], v[150:151], v[110:111], v[18:19]
	v_pk_fma_f32 v[116:117], v[118:119], v[116:117], v[12:13]
	v_pk_fma_f32 v[114:115], v[154:155], v[114:115], v[10:11]
	v_max_f32_e32 v107, 0, v107
	v_max_f32_e32 v106, 0, v106
	v_max_f32_e32 v109, 0, v109
	v_max_f32_e32 v108, 0, v108
	v_pk_mul_f32 v[104:105], v[104:105], v[104:105]
	v_pk_mul_f32 v[102:103], v[102:103], v[102:103]
	v_max_f32_e32 v111, 0, v111
	v_max_f32_e32 v110, 0, v110
	v_max_f32_e32 v113, 0, v113
	v_max_f32_e32 v112, 0, v112
	v_max_f32_e32 v115, 0, v115
	v_max_f32_e32 v114, 0, v114
	v_max_f32_e32 v117, 0, v117
	v_max_f32_e32 v116, 0, v116
	v_pk_mul_f32 v[108:109], v[108:109], v[108:109]
	v_pk_mul_f32 v[106:107], v[106:107], v[106:107]
	v_cvt_pk_bf16_f32 v102, v102, v103
	v_cvt_pk_bf16_f32 v103, v104, v105
	v_pk_mul_f32 v[112:113], v[112:113], v[112:113]
	v_cvt_pk_bf16_f32 v104, v106, v107
	v_cvt_pk_bf16_f32 v105, v108, v109
	v_pk_mul_f32 v[110:111], v[110:111], v[110:111]
	v_pk_mul_f32 v[116:117], v[116:117], v[116:117]
	v_pk_mul_f32 v[114:115], v[114:115], v[114:115]
	global_store_dwordx4 v[120:121], v[102:105], off
	s_nop 1
	v_cvt_pk_bf16_f32 v102, v110, v111
	v_cvt_pk_bf16_f32 v103, v112, v113
	v_cvt_pk_bf16_f32 v104, v114, v115
	v_cvt_pk_bf16_f32 v105, v116, v117
	global_store_dwordx4 v[122:123], v[102:105], off
	s_nop 1
	v_mov_b32_e32 v106, v243
	s_nop 0
	v_add_u32_e32 v103, 0x80, v168
	v_ashrrev_i32_e32 v102, 8, v103
	v_lshlrev_b32_e32 v107, 7, v103
	v_ashrrev_i32_e32 v103, 31, v102
	v_lshlrev_b64 v[104:105], 7, v[102:103]
	v_lshl_add_u64 v[102:103], v[104:105], 0, s[30:31]
	v_lshl_add_u64 v[104:105], v[104:105], 0, s[34:35]
	v_lshlrev_b64 v[102:103], 15, v[102:103]
	v_lshlrev_b64 v[104:105], 15, v[104:105]
	v_lshl_add_u64 v[102:103], s[12:13], 0, v[102:103]
	v_lshl_add_u64 v[104:105], s[12:13], 0, v[104:105]
	v_and_b32_e32 v138, 0x6780, v107
	v_lshl_add_u64 v[108:109], v[102:103], 0, v[138:139]
	v_lshl_add_u64 v[110:111], v[104:105], 0, v[138:139]
	v_lshl_add_u64 v[108:109], v[108:109], 0, v[90:91]
	v_lshl_add_u64 v[110:111], v[110:111], 0, v[90:91]
	s_nop 0
	v_pk_mul_f32 v[112:113], v[6:7], v[106:107] op_sel_hi:[1,0]
	v_pk_mul_f32 v[114:115], v[8:9], v[106:107] op_sel_hi:[1,0]
	v_pk_mul_f32 v[116:117], v[2:3], v[106:107] op_sel_hi:[1,0]
	v_pk_mul_f32 v[118:119], v[4:5], v[106:107] op_sel_hi:[1,0]
	v_pk_fma_f32 v[84:85], v[114:115], v[84:85], v[28:29]
	v_pk_fma_f32 v[82:83], v[112:113], v[82:83], v[26:27]
	v_pk_mul_f32 v[120:121], v[30:31], v[106:107] op_sel_hi:[1,0]
	v_pk_mul_f32 v[122:123], v[32:33], v[106:107] op_sel_hi:[1,0]
	v_pk_mul_f32 v[124:125], v[14:15], v[106:107] op_sel_hi:[1,0]
	v_pk_mul_f32 v[106:107], v[16:17], v[106:107] op_sel_hi:[1,0]
	v_pk_fma_f32 v[88:89], v[118:119], v[88:89], v[24:25]
	v_pk_fma_f32 v[86:87], v[116:117], v[86:87], v[22:23]
	v_max_f32_e32 v83, 0, v83
	v_max_f32_e32 v82, 0, v82
	v_max_f32_e32 v85, 0, v85
	v_max_f32_e32 v84, 0, v84
	v_pk_fma_f32 v[94:95], v[122:123], v[94:95], v[20:21]
	v_pk_fma_f32 v[92:93], v[120:121], v[92:93], v[18:19]
	v_pk_fma_f32 v[98:99], v[106:107], v[98:99], v[12:13]
	v_pk_fma_f32 v[96:97], v[124:125], v[96:97], v[10:11]
	v_max_f32_e32 v87, 0, v87
	v_max_f32_e32 v86, 0, v86
	v_max_f32_e32 v89, 0, v89
	v_max_f32_e32 v88, 0, v88
	v_pk_mul_f32 v[84:85], v[84:85], v[84:85]
	v_pk_mul_f32 v[82:83], v[82:83], v[82:83]
	v_max_f32_e32 v93, 0, v93
	v_max_f32_e32 v92, 0, v92
	v_max_f32_e32 v95, 0, v95
	v_max_f32_e32 v94, 0, v94
	v_max_f32_e32 v97, 0, v97
	v_max_f32_e32 v96, 0, v96
	v_max_f32_e32 v99, 0, v99
	v_max_f32_e32 v98, 0, v98
	v_pk_mul_f32 v[88:89], v[88:89], v[88:89]
	v_pk_mul_f32 v[86:87], v[86:87], v[86:87]
	v_cvt_pk_bf16_f32 v82, v82, v83
	v_cvt_pk_bf16_f32 v83, v84, v85
	v_pk_mul_f32 v[94:95], v[94:95], v[94:95]
	v_cvt_pk_bf16_f32 v84, v86, v87
	v_cvt_pk_bf16_f32 v85, v88, v89
	v_pk_mul_f32 v[92:93], v[92:93], v[92:93]
	v_pk_mul_f32 v[98:99], v[98:99], v[98:99]
	v_pk_mul_f32 v[96:97], v[96:97], v[96:97]
	global_store_dwordx4 v[108:109], v[82:85], off
	s_nop 1
	v_cvt_pk_bf16_f32 v82, v92, v93
	v_cvt_pk_bf16_f32 v83, v94, v95
	v_cvt_pk_bf16_f32 v84, v96, v97
	v_cvt_pk_bf16_f32 v85, v98, v99
	global_store_dwordx4 v[110:111], v[82:85], off
	s_nop 1
	v_mov_b32_e32 v82, v244
	s_nop 0
	v_add_u32_e32 v83, 0x4800, v169
	v_and_b32_e32 v138, 0x6f80, v83
	v_lshl_add_u64 v[84:85], v[102:103], 0, v[138:139]
	v_lshl_add_u64 v[86:87], v[104:105], 0, v[138:139]
	v_lshl_add_u64 v[84:85], v[84:85], 0, v[90:91]
	v_lshl_add_u64 v[86:87], v[86:87], 0, v[90:91]
	s_nop 0
	v_pk_mul_f32 v[88:89], v[6:7], v[82:83] op_sel_hi:[1,0]
	v_pk_mul_f32 v[92:93], v[8:9], v[82:83] op_sel_hi:[1,0]
	v_pk_mul_f32 v[94:95], v[2:3], v[82:83] op_sel_hi:[1,0]
	v_pk_mul_f32 v[96:97], v[4:5], v[82:83] op_sel_hi:[1,0]
	v_pk_fma_f32 v[68:69], v[92:93], v[68:69], v[28:29]
	v_pk_fma_f32 v[66:67], v[88:89], v[66:67], v[26:27]
	v_pk_mul_f32 v[98:99], v[30:31], v[82:83] op_sel_hi:[1,0]
	v_pk_mul_f32 v[106:107], v[32:33], v[82:83] op_sel_hi:[1,0]
	v_pk_mul_f32 v[108:109], v[14:15], v[82:83] op_sel_hi:[1,0]
	v_pk_mul_f32 v[82:83], v[16:17], v[82:83] op_sel_hi:[1,0]
	v_pk_fma_f32 v[72:73], v[96:97], v[72:73], v[24:25]
	v_pk_fma_f32 v[70:71], v[94:95], v[70:71], v[22:23]
	v_max_f32_e32 v67, 0, v67
	v_max_f32_e32 v66, 0, v66
	v_max_f32_e32 v69, 0, v69
	v_max_f32_e32 v68, 0, v68
	v_pk_fma_f32 v[76:77], v[106:107], v[76:77], v[20:21]
	v_pk_fma_f32 v[74:75], v[98:99], v[74:75], v[18:19]
	v_pk_fma_f32 v[80:81], v[82:83], v[80:81], v[12:13]
	v_pk_fma_f32 v[78:79], v[108:109], v[78:79], v[10:11]
	v_max_f32_e32 v71, 0, v71
	v_max_f32_e32 v70, 0, v70
	v_max_f32_e32 v73, 0, v73
	v_max_f32_e32 v72, 0, v72
	v_pk_mul_f32 v[68:69], v[68:69], v[68:69]
	v_pk_mul_f32 v[66:67], v[66:67], v[66:67]
	v_max_f32_e32 v75, 0, v75
	v_max_f32_e32 v74, 0, v74
	v_max_f32_e32 v77, 0, v77
	v_max_f32_e32 v76, 0, v76
	v_max_f32_e32 v79, 0, v79
	v_max_f32_e32 v78, 0, v78
	v_max_f32_e32 v81, 0, v81
	v_max_f32_e32 v80, 0, v80
	v_pk_mul_f32 v[72:73], v[72:73], v[72:73]
	v_pk_mul_f32 v[70:71], v[70:71], v[70:71]
	v_cvt_pk_bf16_f32 v66, v66, v67
	v_cvt_pk_bf16_f32 v67, v68, v69
	v_pk_mul_f32 v[76:77], v[76:77], v[76:77]
	v_cvt_pk_bf16_f32 v68, v70, v71
	v_cvt_pk_bf16_f32 v69, v72, v73
	v_pk_mul_f32 v[74:75], v[74:75], v[74:75]
	v_pk_mul_f32 v[80:81], v[80:81], v[80:81]
	v_pk_mul_f32 v[78:79], v[78:79], v[78:79]
	global_store_dwordx4 v[84:85], v[66:69], off
	s_nop 1
	v_cvt_pk_bf16_f32 v66, v74, v75
	v_cvt_pk_bf16_f32 v67, v76, v77
	v_cvt_pk_bf16_f32 v68, v78, v79
	v_cvt_pk_bf16_f32 v69, v80, v81
	global_store_dwordx4 v[86:87], v[66:69], off
	s_nop 1
	v_mov_b32_e32 v66, v245
	s_nop 0
	v_add_u32_e32 v67, 0x5000, v169
	v_and_b32_e32 v138, 0x7780, v67
	v_lshl_add_u64 v[68:69], v[102:103], 0, v[138:139]
	v_lshl_add_u64 v[70:71], v[104:105], 0, v[138:139]
	v_lshl_add_u64 v[68:69], v[68:69], 0, v[90:91]
	v_lshl_add_u64 v[70:71], v[70:71], 0, v[90:91]
	s_nop 0
	v_pk_mul_f32 v[72:73], v[6:7], v[66:67] op_sel_hi:[1,0]
	v_pk_mul_f32 v[74:75], v[8:9], v[66:67] op_sel_hi:[1,0]
	v_pk_mul_f32 v[76:77], v[2:3], v[66:67] op_sel_hi:[1,0]
	v_pk_mul_f32 v[78:79], v[4:5], v[66:67] op_sel_hi:[1,0]
	v_pk_fma_f32 v[52:53], v[74:75], v[52:53], v[28:29]
	v_pk_fma_f32 v[50:51], v[72:73], v[50:51], v[26:27]
	v_pk_mul_f32 v[80:81], v[30:31], v[66:67] op_sel_hi:[1,0]
	v_pk_mul_f32 v[82:83], v[32:33], v[66:67] op_sel_hi:[1,0]
	v_pk_mul_f32 v[84:85], v[14:15], v[66:67] op_sel_hi:[1,0]
	v_pk_mul_f32 v[66:67], v[16:17], v[66:67] op_sel_hi:[1,0]
	v_pk_fma_f32 v[56:57], v[78:79], v[56:57], v[24:25]
	v_pk_fma_f32 v[54:55], v[76:77], v[54:55], v[22:23]
	v_max_f32_e32 v51, 0, v51
	v_max_f32_e32 v50, 0, v50
	v_max_f32_e32 v53, 0, v53
	v_max_f32_e32 v52, 0, v52
	v_pk_fma_f32 v[60:61], v[82:83], v[60:61], v[20:21]
	v_pk_fma_f32 v[58:59], v[80:81], v[58:59], v[18:19]
	v_pk_fma_f32 v[64:65], v[66:67], v[64:65], v[12:13]
	v_pk_fma_f32 v[62:63], v[84:85], v[62:63], v[10:11]
	v_max_f32_e32 v55, 0, v55
	v_max_f32_e32 v54, 0, v54
	v_max_f32_e32 v57, 0, v57
	v_max_f32_e32 v56, 0, v56
	v_pk_mul_f32 v[52:53], v[52:53], v[52:53]
	v_pk_mul_f32 v[50:51], v[50:51], v[50:51]
	v_max_f32_e32 v59, 0, v59
	v_max_f32_e32 v58, 0, v58
	v_max_f32_e32 v61, 0, v61
	v_max_f32_e32 v60, 0, v60
	v_max_f32_e32 v63, 0, v63
	v_max_f32_e32 v62, 0, v62
	v_max_f32_e32 v65, 0, v65
	v_max_f32_e32 v64, 0, v64
	v_pk_mul_f32 v[56:57], v[56:57], v[56:57]
	v_pk_mul_f32 v[54:55], v[54:55], v[54:55]
	v_cvt_pk_bf16_f32 v50, v50, v51
	v_cvt_pk_bf16_f32 v51, v52, v53
	v_pk_mul_f32 v[60:61], v[60:61], v[60:61]
	v_cvt_pk_bf16_f32 v52, v54, v55
	v_cvt_pk_bf16_f32 v53, v56, v57
	v_pk_mul_f32 v[58:59], v[58:59], v[58:59]
	v_pk_mul_f32 v[64:65], v[64:65], v[64:65]
	v_pk_mul_f32 v[62:63], v[62:63], v[62:63]
	global_store_dwordx4 v[68:69], v[50:53], off
	s_nop 1
	v_cvt_pk_bf16_f32 v50, v58, v59
	v_cvt_pk_bf16_f32 v51, v60, v61
	v_cvt_pk_bf16_f32 v52, v62, v63
	v_cvt_pk_bf16_f32 v53, v64, v65
	global_store_dwordx4 v[70:71], v[50:53], off
	s_nop 1
	v_mov_b32_e32 v50, v246
	s_nop 0
	v_add_u32_e32 v51, 0x5800, v169
	v_and_b32_e32 v138, 0x7f80, v51
	v_lshl_add_u64 v[52:53], v[102:103], 0, v[138:139]
	v_lshl_add_u64 v[54:55], v[104:105], 0, v[138:139]
	v_lshl_add_u64 v[52:53], v[52:53], 0, v[90:91]
	v_lshl_add_u64 v[54:55], v[54:55], 0, v[90:91]
	s_nop 0
	v_pk_mul_f32 v[2:3], v[2:3], v[50:51] op_sel_hi:[1,0]
	v_pk_mul_f32 v[4:5], v[4:5], v[50:51] op_sel_hi:[1,0]
	v_pk_mul_f32 v[6:7], v[6:7], v[50:51] op_sel_hi:[1,0]
	v_pk_mul_f32 v[8:9], v[8:9], v[50:51] op_sel_hi:[1,0]
	v_pk_mul_f32 v[30:31], v[30:31], v[50:51] op_sel_hi:[1,0]
	v_pk_fma_f32 v[4:5], v[4:5], v[40:41], v[24:25]
	v_pk_fma_f32 v[2:3], v[2:3], v[38:39], v[22:23]
	v_pk_mul_f32 v[32:33], v[32:33], v[50:51] op_sel_hi:[1,0]
	v_pk_mul_f32 v[14:15], v[14:15], v[50:51] op_sel_hi:[1,0]
	v_pk_mul_f32 v[16:17], v[16:17], v[50:51] op_sel_hi:[1,0]
	v_pk_fma_f32 v[8:9], v[8:9], v[36:37], v[28:29]
	v_pk_fma_f32 v[6:7], v[6:7], v[34:35], v[26:27]
	v_pk_fma_f32 v[18:19], v[30:31], v[42:43], v[18:19]
	v_max_f32_e32 v3, 0, v3
	v_max_f32_e32 v2, 0, v2
	v_max_f32_e32 v5, 0, v5
	v_max_f32_e32 v4, 0, v4
	v_pk_fma_f32 v[20:21], v[32:33], v[44:45], v[20:21]
	v_pk_fma_f32 v[12:13], v[16:17], v[48:49], v[12:13]
	v_pk_fma_f32 v[10:11], v[14:15], v[46:47], v[10:11]
	v_max_f32_e32 v7, 0, v7
	v_max_f32_e32 v6, 0, v6
	v_max_f32_e32 v9, 0, v9
	v_max_f32_e32 v8, 0, v8
	v_max_f32_e32 v15, 0, v19
	v_max_f32_e32 v14, 0, v18
	v_pk_mul_f32 v[18:19], v[4:5], v[4:5]
	v_pk_mul_f32 v[4:5], v[2:3], v[2:3]
	v_max_f32_e32 v17, 0, v21
	v_max_f32_e32 v16, 0, v20
	v_max_f32_e32 v11, 0, v11
	v_max_f32_e32 v10, 0, v10
	v_max_f32_e32 v13, 0, v13
	v_max_f32_e32 v12, 0, v12
	v_pk_mul_f32 v[8:9], v[8:9], v[8:9]
	v_pk_mul_f32 v[6:7], v[6:7], v[6:7]
	v_pk_mul_f32 v[16:17], v[16:17], v[16:17]
	v_cvt_pk_bf16_f32 v2, v6, v7
	v_cvt_pk_bf16_f32 v3, v8, v9
	v_cvt_pk_bf16_f32 v4, v4, v5
	v_cvt_pk_bf16_f32 v5, v18, v19
	v_pk_mul_f32 v[14:15], v[14:15], v[14:15]
	v_pk_mul_f32 v[12:13], v[12:13], v[12:13]
	v_pk_mul_f32 v[10:11], v[10:11], v[10:11]
	global_store_dwordx4 v[52:53], v[2:5], off
	s_nop 1
	v_cvt_pk_bf16_f32 v2, v14, v15
	v_cvt_pk_bf16_f32 v3, v16, v17
	v_cvt_pk_bf16_f32 v4, v10, v11
	v_cvt_pk_bf16_f32 v5, v12, v13
	global_store_dwordx4 v[54:55], v[2:5], off
	s_cbranch_vccnz .LBB0_1074
	s_andn2_b64 vcc, exec, s[10:11]
	s_cbranch_vccnz .LBB0_1073
	s_barrier
	s_branch .LBB0_1073

.LBB0_1943:
	s_lshl_b32 s26, s30, 8
	s_add_i32 s28, s26, s58
	s_lshl_b32 s26, s31, 8
	s_or_b32 s29, s26, s59
	s_lshr_b32 s26, s30, 4
	s_add_i32 s26, s26, -1
	v_or_b32_e32 v2, s29, v186
	s_cmp_gt_i32 s30, 31
	s_cselect_b32 s26, s26, 0
	v_ashrrev_i32_e32 v3, 31, v2
	v_or_b32_e32 v168, s28, v187
	v_lshlrev_b64 v[10:11], 2, v[2:3]
	v_ashrrev_i32_e32 v169, 31, v168
	s_ashr_i32 s27, s26, 31
	v_lshl_add_u64 v[12:13], s[16:17], 0, v[10:11]
	v_lshl_add_u64 v[100:101], v[168:169], 2, s[14:15]
	s_lshl_b64 s[26:27], s[26:27], 15
	global_load_dwordx4 v[2:5], v[12:13], off offset:16
	global_load_dwordx4 v[6:9], v[12:13], off
	global_load_dword v190, v[100:101], off
	global_load_dword v240, v[100:101], off offset:64
	global_load_dword v241, v[100:101], off offset:128
	global_load_dword v242, v[100:101], off offset:192
	global_load_dword v243, v[100:101], off offset:512
	global_load_dword v244, v[100:101], off offset:576
	global_load_dword v245, v[100:101], off offset:640
	global_load_dword v246, v[100:101], off offset:704
	s_add_u32 s26, s51, s26
	global_load_dwordx4 v[14:17], v[12:13], off offset:528
	global_load_dwordx4 v[30:33], v[12:13], off offset:512
	s_addc_u32 s27, s54, s27
	v_lshl_add_u64 v[10:11], s[26:27], 0, v[10:11]
	global_load_dwordx4 v[26:29], v[10:11], off
	global_load_dwordx4 v[22:25], v[10:11], off offset:16
	global_load_dwordx4 v[18:21], v[10:11], off offset:512
	s_nop 0
	global_load_dwordx4 v[10:13], v[10:11], off offset:528
	s_ashr_i32 s28, s28, 8
	v_bitop3_b32 v90, s29, 56, v186 bitop3:0xc8
	s_ashr_i32 s26, s29, 6
	s_ashr_i32 s29, s28, 31
	s_ashr_i32 s27, s26, 31
	s_lshl_b64 s[34:35], s[28:29], 7
	s_add_u32 s28, s34, s26
	s_addc_u32 s29, s35, s27
	s_lshl_b64 s[28:29], s[28:29], 15
	s_add_u32 s30, s12, s28
	s_addc_u32 s31, s13, s29
	s_or_b32 s28, s26, 2
	s_ashr_i32 s29, s28, 31
	s_add_u32 s34, s34, s28
	v_lshlrev_b32_e32 v169, 7, v168
	s_addc_u32 s35, s35, s29
	v_and_b32_e32 v138, 0x6780, v169
	s_lshl_b64 s[34:35], s[34:35], 15
	v_mov_b32_e32 v91, v139
	v_lshlrev_b32_e32 v90, 1, v90
	v_lshl_add_u64 v[192:193], s[30:31], 0, v[138:139]
	s_add_u32 s34, s12, s34
	v_lshl_add_u64 v[192:193], v[192:193], 0, v[90:91]
	s_addc_u32 s35, s13, s35
	s_and_b64 vcc, exec, s[0:1]
	s_mov_b64 s[0:1], -1
	s_waitcnt vmcnt(0)
	v_pk_mul_f32 v[194:195], v[6:7], v[190:191] op_sel_hi:[1,0]
	v_pk_mul_f32 v[196:197], v[8:9], v[190:191] op_sel_hi:[1,0]
	v_pk_mul_f32 v[198:199], v[2:3], v[190:191] op_sel_hi:[1,0]
	v_pk_mul_f32 v[204:205], v[32:33], v[190:191] op_sel_hi:[1,0]
	v_pk_fma_f32 v[170:171], v[196:197], v[170:171], v[28:29]
	v_pk_fma_f32 v[172:173], v[194:195], v[172:173], v[26:27]
	v_pk_mul_f32 v[200:201], v[4:5], v[190:191] op_sel_hi:[1,0]
	v_pk_mul_f32 v[202:203], v[30:31], v[190:191] op_sel_hi:[1,0]
	v_pk_mul_f32 v[206:207], v[14:15], v[190:191] op_sel_hi:[1,0]
	v_pk_mul_f32 v[190:191], v[16:17], v[190:191] op_sel_hi:[1,0]
	v_pk_fma_f32 v[174:175], v[198:199], v[174:175], v[22:23]
	v_pk_fma_f32 v[182:183], v[204:205], v[182:183], v[20:21]
	v_max_f32_e32 v173, 0, v173
	v_max_f32_e32 v172, 0, v172
	v_max_f32_e32 v171, 0, v171
	v_max_f32_e32 v170, 0, v170
	v_pk_fma_f32 v[176:177], v[200:201], v[176:177], v[24:25]
	v_pk_fma_f32 v[180:181], v[202:203], v[180:181], v[18:19]
	v_pk_fma_f32 v[184:185], v[190:191], v[184:185], v[12:13]
	v_max_f32_e32 v175, 0, v175
	v_max_f32_e32 v174, 0, v174
	v_max_f32_e32 v183, 0, v183
	v_max_f32_e32 v182, 0, v182
	v_pk_mul_f32 v[190:191], v[170:171], v[170:171]
	v_pk_mul_f32 v[170:171], v[172:173], v[172:173]
	v_max_f32_e32 v177, 0, v177
	v_max_f32_e32 v176, 0, v176
	v_max_f32_e32 v181, 0, v181
	v_max_f32_e32 v180, 0, v180
	v_pk_mul_f32 v[172:173], v[174:175], v[174:175]
	v_pk_mul_f32 v[174:175], v[182:183], v[182:183]
	v_cvt_pk_bf16_f32 v170, v170, v171
	v_cvt_pk_bf16_f32 v171, v190, v191
	v_pk_fma_f32 v[178:179], v[206:207], v[178:179], v[10:11]
	v_pk_mul_f32 v[176:177], v[176:177], v[176:177]
	v_pk_mul_f32 v[180:181], v[180:181], v[180:181]
	v_cvt_pk_bf16_f32 v172, v172, v173
	v_cvt_pk_bf16_f32 v173, v176, v177
	global_store_dwordx4 v[192:193], v[170:173], off
	v_max_f32_e32 v179, 0, v179
	v_max_f32_e32 v178, 0, v178
	v_cvt_pk_bf16_f32 v170, v180, v181
	v_cvt_pk_bf16_f32 v171, v174, v175
	v_lshl_add_u64 v[174:175], s[34:35], 0, v[138:139]
	v_max_f32_e32 v185, 0, v185
	v_max_f32_e32 v184, 0, v184
	v_lshl_add_u64 v[174:175], v[174:175], 0, v[90:91]
	v_pk_mul_f32 v[182:183], v[184:185], v[184:185]
	v_pk_mul_f32 v[178:179], v[178:179], v[178:179]
	s_nop 0
	v_cvt_pk_bf16_f32 v172, v178, v179
	v_cvt_pk_bf16_f32 v173, v182, v183
	global_store_dwordx4 v[174:175], v[170:173], off
	v_or_b32_e32 v174, 32, v168
	v_ashrrev_i32_e32 v175, 31, v174
	v_or_b32_e32 v170, 16, v168
	v_ashrrev_i32_e32 v171, 31, v170
	v_lshl_add_u64 v[172:173], v[170:171], 2, s[14:15]
	s_nop 1
	v_mov_b32_e32 v172, v240
	v_lshlrev_b32_e32 v138, 7, v170
	v_and_b32_e32 v138, 0x6f80, v138
	v_lshl_add_u64 v[176:177], s[30:31], 0, v[138:139]
	v_lshl_add_u64 v[178:179], s[34:35], 0, v[138:139]
	v_lshl_add_u64 v[176:177], v[176:177], 0, v[90:91]
	v_lshl_add_u64 v[178:179], v[178:179], 0, v[90:91]
	v_lshl_add_u64 v[170:171], v[174:175], 2, s[14:15]
	v_lshlrev_b32_e32 v138, 7, v174
	v_and_b32_e32 v138, 0x7780, v138
	s_nop 0
	v_pk_mul_f32 v[180:181], v[6:7], v[172:173] op_sel_hi:[1,0]
	v_pk_mul_f32 v[182:183], v[8:9], v[172:173] op_sel_hi:[1,0]
	v_pk_mul_f32 v[184:185], v[2:3], v[172:173] op_sel_hi:[1,0]
	v_pk_mul_f32 v[190:191], v[4:5], v[172:173] op_sel_hi:[1,0]
	v_pk_fma_f32 v[154:155], v[182:183], v[154:155], v[28:29]
	v_pk_fma_f32 v[152:153], v[180:181], v[152:153], v[26:27]
	v_pk_mul_f32 v[192:193], v[30:31], v[172:173] op_sel_hi:[1,0]
	v_pk_mul_f32 v[194:195], v[32:33], v[172:173] op_sel_hi:[1,0]
	v_pk_mul_f32 v[196:197], v[14:15], v[172:173] op_sel_hi:[1,0]
	v_pk_mul_f32 v[172:173], v[16:17], v[172:173] op_sel_hi:[1,0]
	v_pk_fma_f32 v[158:159], v[190:191], v[158:159], v[24:25]
	v_pk_fma_f32 v[156:157], v[184:185], v[156:157], v[22:23]
	v_max_f32_e32 v153, 0, v153
	v_max_f32_e32 v152, 0, v152
	v_max_f32_e32 v155, 0, v155
	v_max_f32_e32 v154, 0, v154
	v_pk_fma_f32 v[162:163], v[194:195], v[162:163], v[20:21]
	v_pk_fma_f32 v[160:161], v[192:193], v[160:161], v[18:19]
	v_pk_fma_f32 v[166:167], v[172:173], v[166:167], v[12:13]
	v_pk_fma_f32 v[164:165], v[196:197], v[164:165], v[10:11]
	v_max_f32_e32 v157, 0, v157
	v_max_f32_e32 v156, 0, v156
	v_max_f32_e32 v159, 0, v159
	v_max_f32_e32 v158, 0, v158
	v_pk_mul_f32 v[154:155], v[154:155], v[154:155]
	v_pk_mul_f32 v[152:153], v[152:153], v[152:153]
	v_max_f32_e32 v161, 0, v161
	v_max_f32_e32 v160, 0, v160
	v_max_f32_e32 v163, 0, v163
	v_max_f32_e32 v162, 0, v162
	v_max_f32_e32 v165, 0, v165
	v_max_f32_e32 v164, 0, v164
	v_max_f32_e32 v167, 0, v167
	v_max_f32_e32 v166, 0, v166
	v_pk_mul_f32 v[158:159], v[158:159], v[158:159]
	v_pk_mul_f32 v[156:157], v[156:157], v[156:157]
	v_cvt_pk_bf16_f32 v152, v152, v153
	v_cvt_pk_bf16_f32 v153, v154, v155
	v_pk_mul_f32 v[162:163], v[162:163], v[162:163]
	v_cvt_pk_bf16_f32 v154, v156, v157
	v_cvt_pk_bf16_f32 v155, v158, v159
	v_pk_mul_f32 v[160:161], v[160:161], v[160:161]
	v_pk_mul_f32 v[166:167], v[166:167], v[166:167]
	v_pk_mul_f32 v[164:165], v[164:165], v[164:165]
	global_store_dwordx4 v[176:177], v[152:155], off
	v_lshl_add_u64 v[158:159], s[30:31], 0, v[138:139]
	v_lshl_add_u64 v[158:159], v[158:159], 0, v[90:91]
	v_cvt_pk_bf16_f32 v152, v160, v161
	v_cvt_pk_bf16_f32 v153, v162, v163
	v_cvt_pk_bf16_f32 v154, v164, v165
	v_cvt_pk_bf16_f32 v155, v166, v167
	global_store_dwordx4 v[178:179], v[152:155], off
	s_nop 1
	v_mov_b32_e32 v152, v241
	v_lshl_add_u64 v[160:161], s[34:35], 0, v[138:139]
	v_or_b32_e32 v154, 48, v168
	v_ashrrev_i32_e32 v155, 31, v154
	v_lshl_add_u64 v[160:161], v[160:161], 0, v[90:91]
	v_lshl_add_u64 v[156:157], v[154:155], 2, s[14:15]
	s_nop 0
	v_pk_mul_f32 v[162:163], v[6:7], v[152:153] op_sel_hi:[1,0]
	v_pk_mul_f32 v[164:165], v[8:9], v[152:153] op_sel_hi:[1,0]
	v_pk_mul_f32 v[166:167], v[2:3], v[152:153] op_sel_hi:[1,0]
	v_pk_mul_f32 v[170:171], v[4:5], v[152:153] op_sel_hi:[1,0]
	v_pk_fma_f32 v[120:121], v[164:165], v[120:121], v[28:29]
	v_pk_fma_f32 v[118:119], v[162:163], v[118:119], v[26:27]
	v_pk_mul_f32 v[172:173], v[30:31], v[152:153] op_sel_hi:[1,0]
	v_pk_mul_f32 v[174:175], v[32:33], v[152:153] op_sel_hi:[1,0]
	v_pk_mul_f32 v[176:177], v[14:15], v[152:153] op_sel_hi:[1,0]
	v_pk_mul_f32 v[152:153], v[16:17], v[152:153] op_sel_hi:[1,0]
	v_pk_fma_f32 v[124:125], v[170:171], v[124:125], v[24:25]
	v_pk_fma_f32 v[122:123], v[166:167], v[122:123], v[22:23]
	v_max_f32_e32 v119, 0, v119
	v_max_f32_e32 v118, 0, v118
	v_max_f32_e32 v121, 0, v121
	v_max_f32_e32 v120, 0, v120
	v_pk_fma_f32 v[128:129], v[174:175], v[128:129], v[20:21]
	v_pk_fma_f32 v[126:127], v[172:173], v[126:127], v[18:19]
	v_pk_fma_f32 v[150:151], v[152:153], v[150:151], v[12:13]
	v_pk_fma_f32 v[148:149], v[176:177], v[148:149], v[10:11]
	v_max_f32_e32 v123, 0, v123
	v_max_f32_e32 v122, 0, v122
	v_max_f32_e32 v125, 0, v125
	v_max_f32_e32 v124, 0, v124
	v_pk_mul_f32 v[120:121], v[120:121], v[120:121]
	v_pk_mul_f32 v[118:119], v[118:119], v[118:119]
	v_max_f32_e32 v127, 0, v127
	v_max_f32_e32 v126, 0, v126
	v_max_f32_e32 v129, 0, v129
	v_max_f32_e32 v128, 0, v128
	v_max_f32_e32 v149, 0, v149
	v_max_f32_e32 v148, 0, v148
	v_max_f32_e32 v151, 0, v151
	v_max_f32_e32 v150, 0, v150
	v_pk_mul_f32 v[124:125], v[124:125], v[124:125]
	v_pk_mul_f32 v[122:123], v[122:123], v[122:123]
	v_cvt_pk_bf16_f32 v118, v118, v119
	v_cvt_pk_bf16_f32 v119, v120, v121
	v_pk_mul_f32 v[128:129], v[128:129], v[128:129]
	v_cvt_pk_bf16_f32 v120, v122, v123
	v_cvt_pk_bf16_f32 v121, v124, v125
	v_pk_mul_f32 v[126:127], v[126:127], v[126:127]
	v_pk_mul_f32 v[150:151], v[150:151], v[150:151]
	v_pk_mul_f32 v[148:149], v[148:149], v[148:149]
	global_store_dwordx4 v[158:159], v[118:121], off
	s_nop 1
	v_cvt_pk_bf16_f32 v118, v126, v127
	v_cvt_pk_bf16_f32 v119, v128, v129
	v_cvt_pk_bf16_f32 v120, v148, v149
	v_cvt_pk_bf16_f32 v121, v150, v151
	global_store_dwordx4 v[160:161], v[118:121], off
	s_nop 1
	v_mov_b32_e32 v118, v242
	s_nop 0
	v_lshlrev_b32_e32 v119, 7, v154
	v_and_b32_e32 v138, 0x7f80, v119
	v_lshl_add_u64 v[120:121], s[30:31], 0, v[138:139]
	v_lshl_add_u64 v[122:123], s[34:35], 0, v[138:139]
	v_lshl_add_u64 v[120:121], v[120:121], 0, v[90:91]
	v_lshl_add_u64 v[122:123], v[122:123], 0, v[90:91]
	s_nop 0
	v_pk_mul_f32 v[124:125], v[6:7], v[118:119] op_sel_hi:[1,0]
	v_pk_mul_f32 v[126:127], v[8:9], v[118:119] op_sel_hi:[1,0]
	v_pk_mul_f32 v[128:129], v[2:3], v[118:119] op_sel_hi:[1,0]
	v_pk_mul_f32 v[148:149], v[4:5], v[118:119] op_sel_hi:[1,0]
	v_pk_fma_f32 v[104:105], v[126:127], v[104:105], v[28:29]
	v_pk_fma_f32 v[102:103], v[124:125], v[102:103], v[26:27]
	v_pk_mul_f32 v[150:151], v[30:31], v[118:119] op_sel_hi:[1,0]
	v_pk_mul_f32 v[152:153], v[32:33], v[118:119] op_sel_hi:[1,0]
	v_pk_mul_f32 v[154:155], v[14:15], v[118:119] op_sel_hi:[1,0]
	v_pk_mul_f32 v[118:119], v[16:17], v[118:119] op_sel_hi:[1,0]
	v_pk_fma_f32 v[108:109], v[148:149], v[108:109], v[24:25]
	v_pk_fma_f32 v[106:107], v[128:129], v[106:107], v[22:23]
	v_max_f32_e32 v103, 0, v103
	v_max_f32_e32 v102, 0, v102
	v_max_f32_e32 v105, 0, v105
	v_max_f32_e32 v104, 0, v104
	v_pk_fma_f32 v[112:113], v[152:153], v[112:113], v[20:21]
	v_pk_fma_f32 v[110:111], v[150:151], v[110:111], v[18:19]
	v_pk_fma_f32 v[116:117], v[118:119], v[116:117], v[12:13]
	v_pk_fma_f32 v[114:115], v[154:155], v[114:115], v[10:11]
	v_max_f32_e32 v107, 0, v107
	v_max_f32_e32 v106, 0, v106
	v_max_f32_e32 v109, 0, v109
	v_max_f32_e32 v108, 0, v108
	v_pk_mul_f32 v[104:105], v[104:105], v[104:105]
	v_pk_mul_f32 v[102:103], v[102:103], v[102:103]
	v_max_f32_e32 v111, 0, v111
	v_max_f32_e32 v110, 0, v110
	v_max_f32_e32 v113, 0, v113
	v_max_f32_e32 v112, 0, v112
	v_max_f32_e32 v115, 0, v115
	v_max_f32_e32 v114, 0, v114
	v_max_f32_e32 v117, 0, v117
	v_max_f32_e32 v116, 0, v116
	v_pk_mul_f32 v[108:109], v[108:109], v[108:109]
	v_pk_mul_f32 v[106:107], v[106:107], v[106:107]
	v_cvt_pk_bf16_f32 v102, v102, v103
	v_cvt_pk_bf16_f32 v103, v104, v105
	v_pk_mul_f32 v[112:113], v[112:113], v[112:113]
	v_cvt_pk_bf16_f32 v104, v106, v107
	v_cvt_pk_bf16_f32 v105, v108, v109
	v_pk_mul_f32 v[110:111], v[110:111], v[110:111]
	v_pk_mul_f32 v[116:117], v[116:117], v[116:117]
	v_pk_mul_f32 v[114:115], v[114:115], v[114:115]
	global_store_dwordx4 v[120:121], v[102:105], off
	s_nop 1
	v_cvt_pk_bf16_f32 v102, v110, v111
	v_cvt_pk_bf16_f32 v103, v112, v113
	v_cvt_pk_bf16_f32 v104, v114, v115
	v_cvt_pk_bf16_f32 v105, v116, v117
	global_store_dwordx4 v[122:123], v[102:105], off
	s_nop 1
	v_mov_b32_e32 v106, v243
	s_nop 0
	v_add_u32_e32 v103, 0x80, v168
	v_ashrrev_i32_e32 v102, 8, v103
	v_lshlrev_b32_e32 v107, 7, v103
	v_ashrrev_i32_e32 v103, 31, v102
	v_lshlrev_b64 v[104:105], 7, v[102:103]
	v_lshl_add_u64 v[102:103], v[104:105], 0, s[26:27]
	v_lshl_add_u64 v[104:105], v[104:105], 0, s[28:29]
	v_lshlrev_b64 v[102:103], 15, v[102:103]
	v_lshlrev_b64 v[104:105], 15, v[104:105]
	v_lshl_add_u64 v[102:103], s[12:13], 0, v[102:103]
	v_lshl_add_u64 v[104:105], s[12:13], 0, v[104:105]
	v_and_b32_e32 v138, 0x6780, v107
	v_lshl_add_u64 v[108:109], v[102:103], 0, v[138:139]
	v_lshl_add_u64 v[110:111], v[104:105], 0, v[138:139]
	v_lshl_add_u64 v[108:109], v[108:109], 0, v[90:91]
	v_lshl_add_u64 v[110:111], v[110:111], 0, v[90:91]
	s_nop 0
	v_pk_mul_f32 v[112:113], v[6:7], v[106:107] op_sel_hi:[1,0]
	v_pk_mul_f32 v[114:115], v[8:9], v[106:107] op_sel_hi:[1,0]
	v_pk_mul_f32 v[116:117], v[2:3], v[106:107] op_sel_hi:[1,0]
	v_pk_mul_f32 v[118:119], v[4:5], v[106:107] op_sel_hi:[1,0]
	v_pk_fma_f32 v[84:85], v[114:115], v[84:85], v[28:29]
	v_pk_fma_f32 v[82:83], v[112:113], v[82:83], v[26:27]
	v_pk_mul_f32 v[120:121], v[30:31], v[106:107] op_sel_hi:[1,0]
	v_pk_mul_f32 v[122:123], v[32:33], v[106:107] op_sel_hi:[1,0]
	v_pk_mul_f32 v[124:125], v[14:15], v[106:107] op_sel_hi:[1,0]
	v_pk_mul_f32 v[106:107], v[16:17], v[106:107] op_sel_hi:[1,0]
	v_pk_fma_f32 v[88:89], v[118:119], v[88:89], v[24:25]
	v_pk_fma_f32 v[86:87], v[116:117], v[86:87], v[22:23]
	v_max_f32_e32 v83, 0, v83
	v_max_f32_e32 v82, 0, v82
	v_max_f32_e32 v85, 0, v85
	v_max_f32_e32 v84, 0, v84
	v_pk_fma_f32 v[94:95], v[122:123], v[94:95], v[20:21]
	v_pk_fma_f32 v[92:93], v[120:121], v[92:93], v[18:19]
	v_pk_fma_f32 v[98:99], v[106:107], v[98:99], v[12:13]
	v_pk_fma_f32 v[96:97], v[124:125], v[96:97], v[10:11]
	v_max_f32_e32 v87, 0, v87
	v_max_f32_e32 v86, 0, v86
	v_max_f32_e32 v89, 0, v89
	v_max_f32_e32 v88, 0, v88
	v_pk_mul_f32 v[84:85], v[84:85], v[84:85]
	v_pk_mul_f32 v[82:83], v[82:83], v[82:83]
	v_max_f32_e32 v93, 0, v93
	v_max_f32_e32 v92, 0, v92
	v_max_f32_e32 v95, 0, v95
	v_max_f32_e32 v94, 0, v94
	v_max_f32_e32 v97, 0, v97
	v_max_f32_e32 v96, 0, v96
	v_max_f32_e32 v99, 0, v99
	v_max_f32_e32 v98, 0, v98
	v_pk_mul_f32 v[88:89], v[88:89], v[88:89]
	v_pk_mul_f32 v[86:87], v[86:87], v[86:87]
	v_cvt_pk_bf16_f32 v82, v82, v83
	v_cvt_pk_bf16_f32 v83, v84, v85
	v_pk_mul_f32 v[94:95], v[94:95], v[94:95]
	v_cvt_pk_bf16_f32 v84, v86, v87
	v_cvt_pk_bf16_f32 v85, v88, v89
	v_pk_mul_f32 v[92:93], v[92:93], v[92:93]
	v_pk_mul_f32 v[98:99], v[98:99], v[98:99]
	v_pk_mul_f32 v[96:97], v[96:97], v[96:97]
	global_store_dwordx4 v[108:109], v[82:85], off
	s_nop 1
	v_cvt_pk_bf16_f32 v82, v92, v93
	v_cvt_pk_bf16_f32 v83, v94, v95
	v_cvt_pk_bf16_f32 v84, v96, v97
	v_cvt_pk_bf16_f32 v85, v98, v99
	global_store_dwordx4 v[110:111], v[82:85], off
	s_nop 1
	v_mov_b32_e32 v82, v244
	s_nop 0
	v_add_u32_e32 v83, 0x4800, v169
	v_and_b32_e32 v138, 0x6f80, v83
	v_lshl_add_u64 v[84:85], v[102:103], 0, v[138:139]
	v_lshl_add_u64 v[86:87], v[104:105], 0, v[138:139]
	v_lshl_add_u64 v[84:85], v[84:85], 0, v[90:91]
	v_lshl_add_u64 v[86:87], v[86:87], 0, v[90:91]
	s_nop 0
	v_pk_mul_f32 v[88:89], v[6:7], v[82:83] op_sel_hi:[1,0]
	v_pk_mul_f32 v[92:93], v[8:9], v[82:83] op_sel_hi:[1,0]
	v_pk_mul_f32 v[94:95], v[2:3], v[82:83] op_sel_hi:[1,0]
	v_pk_mul_f32 v[96:97], v[4:5], v[82:83] op_sel_hi:[1,0]
	v_pk_fma_f32 v[68:69], v[92:93], v[68:69], v[28:29]
	v_pk_fma_f32 v[66:67], v[88:89], v[66:67], v[26:27]
	v_pk_mul_f32 v[98:99], v[30:31], v[82:83] op_sel_hi:[1,0]
	v_pk_mul_f32 v[106:107], v[32:33], v[82:83] op_sel_hi:[1,0]
	v_pk_mul_f32 v[108:109], v[14:15], v[82:83] op_sel_hi:[1,0]
	v_pk_mul_f32 v[82:83], v[16:17], v[82:83] op_sel_hi:[1,0]
	v_pk_fma_f32 v[72:73], v[96:97], v[72:73], v[24:25]
	v_pk_fma_f32 v[70:71], v[94:95], v[70:71], v[22:23]
	v_max_f32_e32 v67, 0, v67
	v_max_f32_e32 v66, 0, v66
	v_max_f32_e32 v69, 0, v69
	v_max_f32_e32 v68, 0, v68
	v_pk_fma_f32 v[76:77], v[106:107], v[76:77], v[20:21]
	v_pk_fma_f32 v[74:75], v[98:99], v[74:75], v[18:19]
	v_pk_fma_f32 v[80:81], v[82:83], v[80:81], v[12:13]
	v_pk_fma_f32 v[78:79], v[108:109], v[78:79], v[10:11]
	v_max_f32_e32 v71, 0, v71
	v_max_f32_e32 v70, 0, v70
	v_max_f32_e32 v73, 0, v73
	v_max_f32_e32 v72, 0, v72
	v_pk_mul_f32 v[68:69], v[68:69], v[68:69]
	v_pk_mul_f32 v[66:67], v[66:67], v[66:67]
	v_max_f32_e32 v75, 0, v75
	v_max_f32_e32 v74, 0, v74
	v_max_f32_e32 v77, 0, v77
	v_max_f32_e32 v76, 0, v76
	v_max_f32_e32 v79, 0, v79
	v_max_f32_e32 v78, 0, v78
	v_max_f32_e32 v81, 0, v81
	v_max_f32_e32 v80, 0, v80
	v_pk_mul_f32 v[72:73], v[72:73], v[72:73]
	v_pk_mul_f32 v[70:71], v[70:71], v[70:71]
	v_cvt_pk_bf16_f32 v66, v66, v67
	v_cvt_pk_bf16_f32 v67, v68, v69
	v_pk_mul_f32 v[76:77], v[76:77], v[76:77]
	v_cvt_pk_bf16_f32 v68, v70, v71
	v_cvt_pk_bf16_f32 v69, v72, v73
	v_pk_mul_f32 v[74:75], v[74:75], v[74:75]
	v_pk_mul_f32 v[80:81], v[80:81], v[80:81]
	v_pk_mul_f32 v[78:79], v[78:79], v[78:79]
	global_store_dwordx4 v[84:85], v[66:69], off
	s_nop 1
	v_cvt_pk_bf16_f32 v66, v74, v75
	v_cvt_pk_bf16_f32 v67, v76, v77
	v_cvt_pk_bf16_f32 v68, v78, v79
	v_cvt_pk_bf16_f32 v69, v80, v81
	global_store_dwordx4 v[86:87], v[66:69], off
	s_nop 1
	v_mov_b32_e32 v66, v245
	s_nop 0
	v_add_u32_e32 v67, 0x5000, v169
	v_and_b32_e32 v138, 0x7780, v67
	v_lshl_add_u64 v[68:69], v[102:103], 0, v[138:139]
	v_lshl_add_u64 v[70:71], v[104:105], 0, v[138:139]
	v_lshl_add_u64 v[68:69], v[68:69], 0, v[90:91]
	v_lshl_add_u64 v[70:71], v[70:71], 0, v[90:91]
	s_nop 0
	v_pk_mul_f32 v[72:73], v[6:7], v[66:67] op_sel_hi:[1,0]
	v_pk_mul_f32 v[74:75], v[8:9], v[66:67] op_sel_hi:[1,0]
	v_pk_mul_f32 v[76:77], v[2:3], v[66:67] op_sel_hi:[1,0]
	v_pk_mul_f32 v[78:79], v[4:5], v[66:67] op_sel_hi:[1,0]
	v_pk_fma_f32 v[52:53], v[74:75], v[52:53], v[28:29]
	v_pk_fma_f32 v[50:51], v[72:73], v[50:51], v[26:27]
	v_pk_mul_f32 v[80:81], v[30:31], v[66:67] op_sel_hi:[1,0]
	v_pk_mul_f32 v[82:83], v[32:33], v[66:67] op_sel_hi:[1,0]
	v_pk_mul_f32 v[84:85], v[14:15], v[66:67] op_sel_hi:[1,0]
	v_pk_mul_f32 v[66:67], v[16:17], v[66:67] op_sel_hi:[1,0]
	v_pk_fma_f32 v[56:57], v[78:79], v[56:57], v[24:25]
	v_pk_fma_f32 v[54:55], v[76:77], v[54:55], v[22:23]
	v_max_f32_e32 v51, 0, v51
	v_max_f32_e32 v50, 0, v50
	v_max_f32_e32 v53, 0, v53
	v_max_f32_e32 v52, 0, v52
	v_pk_fma_f32 v[60:61], v[82:83], v[60:61], v[20:21]
	v_pk_fma_f32 v[58:59], v[80:81], v[58:59], v[18:19]
	v_pk_fma_f32 v[64:65], v[66:67], v[64:65], v[12:13]
	v_pk_fma_f32 v[62:63], v[84:85], v[62:63], v[10:11]
	v_max_f32_e32 v55, 0, v55
	v_max_f32_e32 v54, 0, v54
	v_max_f32_e32 v57, 0, v57
	v_max_f32_e32 v56, 0, v56
	v_pk_mul_f32 v[52:53], v[52:53], v[52:53]
	v_pk_mul_f32 v[50:51], v[50:51], v[50:51]
	v_max_f32_e32 v59, 0, v59
	v_max_f32_e32 v58, 0, v58
	v_max_f32_e32 v61, 0, v61
	v_max_f32_e32 v60, 0, v60
	v_max_f32_e32 v63, 0, v63
	v_max_f32_e32 v62, 0, v62
	v_max_f32_e32 v65, 0, v65
	v_max_f32_e32 v64, 0, v64
	v_pk_mul_f32 v[56:57], v[56:57], v[56:57]
	v_pk_mul_f32 v[54:55], v[54:55], v[54:55]
	v_cvt_pk_bf16_f32 v50, v50, v51
	v_cvt_pk_bf16_f32 v51, v52, v53
	v_pk_mul_f32 v[60:61], v[60:61], v[60:61]
	v_cvt_pk_bf16_f32 v52, v54, v55
	v_cvt_pk_bf16_f32 v53, v56, v57
	v_pk_mul_f32 v[58:59], v[58:59], v[58:59]
	v_pk_mul_f32 v[64:65], v[64:65], v[64:65]
	v_pk_mul_f32 v[62:63], v[62:63], v[62:63]
	global_store_dwordx4 v[68:69], v[50:53], off
	s_nop 1
	v_cvt_pk_bf16_f32 v50, v58, v59
	v_cvt_pk_bf16_f32 v51, v60, v61
	v_cvt_pk_bf16_f32 v52, v62, v63
	v_cvt_pk_bf16_f32 v53, v64, v65
	global_store_dwordx4 v[70:71], v[50:53], off
	s_nop 1
	v_mov_b32_e32 v50, v246
	s_nop 0
	v_add_u32_e32 v51, 0x5800, v169
	v_and_b32_e32 v138, 0x7f80, v51
	v_lshl_add_u64 v[52:53], v[102:103], 0, v[138:139]
	v_lshl_add_u64 v[54:55], v[104:105], 0, v[138:139]
	v_lshl_add_u64 v[52:53], v[52:53], 0, v[90:91]
	v_lshl_add_u64 v[54:55], v[54:55], 0, v[90:91]
	s_nop 0
	v_pk_mul_f32 v[2:3], v[2:3], v[50:51] op_sel_hi:[1,0]
	v_pk_mul_f32 v[4:5], v[4:5], v[50:51] op_sel_hi:[1,0]
	v_pk_mul_f32 v[6:7], v[6:7], v[50:51] op_sel_hi:[1,0]
	v_pk_mul_f32 v[8:9], v[8:9], v[50:51] op_sel_hi:[1,0]
	v_pk_mul_f32 v[30:31], v[30:31], v[50:51] op_sel_hi:[1,0]
	v_pk_fma_f32 v[4:5], v[4:5], v[40:41], v[24:25]
	v_pk_fma_f32 v[2:3], v[2:3], v[38:39], v[22:23]
	v_pk_mul_f32 v[32:33], v[32:33], v[50:51] op_sel_hi:[1,0]
	v_pk_mul_f32 v[14:15], v[14:15], v[50:51] op_sel_hi:[1,0]
	v_pk_mul_f32 v[16:17], v[16:17], v[50:51] op_sel_hi:[1,0]
	v_pk_fma_f32 v[8:9], v[8:9], v[36:37], v[28:29]
	v_pk_fma_f32 v[6:7], v[6:7], v[34:35], v[26:27]
	v_pk_fma_f32 v[18:19], v[30:31], v[42:43], v[18:19]
	v_max_f32_e32 v3, 0, v3
	v_max_f32_e32 v2, 0, v2
	v_max_f32_e32 v5, 0, v5
	v_max_f32_e32 v4, 0, v4
	v_pk_fma_f32 v[20:21], v[32:33], v[44:45], v[20:21]
	v_pk_fma_f32 v[12:13], v[16:17], v[48:49], v[12:13]
	v_pk_fma_f32 v[10:11], v[14:15], v[46:47], v[10:11]
	v_max_f32_e32 v7, 0, v7
	v_max_f32_e32 v6, 0, v6
	v_max_f32_e32 v9, 0, v9
	v_max_f32_e32 v8, 0, v8
	v_max_f32_e32 v15, 0, v19
	v_max_f32_e32 v14, 0, v18
	v_pk_mul_f32 v[18:19], v[4:5], v[4:5]
	v_pk_mul_f32 v[4:5], v[2:3], v[2:3]
	v_max_f32_e32 v17, 0, v21
	v_max_f32_e32 v16, 0, v20
	v_max_f32_e32 v11, 0, v11
	v_max_f32_e32 v10, 0, v10
	v_max_f32_e32 v13, 0, v13
	v_max_f32_e32 v12, 0, v12
	v_pk_mul_f32 v[8:9], v[8:9], v[8:9]
	v_pk_mul_f32 v[6:7], v[6:7], v[6:7]
	v_pk_mul_f32 v[16:17], v[16:17], v[16:17]
	v_cvt_pk_bf16_f32 v2, v6, v7
	v_cvt_pk_bf16_f32 v3, v8, v9
	v_cvt_pk_bf16_f32 v4, v4, v5
	v_cvt_pk_bf16_f32 v5, v18, v19
	v_pk_mul_f32 v[14:15], v[14:15], v[14:15]
	v_pk_mul_f32 v[12:13], v[12:13], v[12:13]
	v_pk_mul_f32 v[10:11], v[10:11], v[10:11]
	global_store_dwordx4 v[52:53], v[2:5], off
	s_nop 1
	v_cvt_pk_bf16_f32 v2, v14, v15
	v_cvt_pk_bf16_f32 v3, v16, v17
	v_cvt_pk_bf16_f32 v4, v10, v11
	v_cvt_pk_bf16_f32 v5, v12, v13
	global_store_dwordx4 v[54:55], v[2:5], off
	s_cbranch_vccnz .LBB0_1926
	s_andn2_b64 vcc, exec, s[10:11]
	s_cbranch_vccnz .LBB0_1925
	s_barrier
	s_branch .LBB0_1925

.LBB0_2953:
	s_lshl_b32 s26, s30, 8
	s_add_i32 s28, s26, s56
	s_lshl_b32 s26, s31, 8
	s_or_b32 s29, s26, s57
	s_lshr_b32 s26, s30, 4
	s_add_i32 s26, s26, -1
	v_or_b32_e32 v2, s29, v186
	s_cmp_gt_i32 s30, 31
	s_cselect_b32 s26, s26, 0
	v_ashrrev_i32_e32 v3, 31, v2
	v_or_b32_e32 v168, s28, v187
	v_lshlrev_b64 v[10:11], 2, v[2:3]
	v_ashrrev_i32_e32 v169, 31, v168
	s_ashr_i32 s27, s26, 31
	v_lshl_add_u64 v[12:13], s[16:17], 0, v[10:11]
	v_lshl_add_u64 v[100:101], v[168:169], 2, s[14:15]
	s_lshl_b64 s[26:27], s[26:27], 15
	global_load_dwordx4 v[2:5], v[12:13], off offset:16
	global_load_dwordx4 v[6:9], v[12:13], off
	global_load_dword v190, v[100:101], off
	global_load_dword v240, v[100:101], off offset:64
	global_load_dword v241, v[100:101], off offset:128
	global_load_dword v242, v[100:101], off offset:192
	global_load_dword v243, v[100:101], off offset:512
	global_load_dword v244, v[100:101], off offset:576
	global_load_dword v245, v[100:101], off offset:640
	global_load_dword v246, v[100:101], off offset:704
	s_add_u32 s26, s47, s26
	global_load_dwordx4 v[14:17], v[12:13], off offset:528
	global_load_dwordx4 v[30:33], v[12:13], off offset:512
	s_addc_u32 s27, s50, s27
	v_lshl_add_u64 v[10:11], s[26:27], 0, v[10:11]
	global_load_dwordx4 v[26:29], v[10:11], off
	global_load_dwordx4 v[22:25], v[10:11], off offset:16
	global_load_dwordx4 v[18:21], v[10:11], off offset:512
	s_nop 0
	global_load_dwordx4 v[10:13], v[10:11], off offset:528
	s_ashr_i32 s28, s28, 8
	v_bitop3_b32 v90, s29, 56, v186 bitop3:0xc8
	s_ashr_i32 s26, s29, 6
	s_ashr_i32 s29, s28, 31
	s_ashr_i32 s27, s26, 31
	s_lshl_b64 s[34:35], s[28:29], 7
	s_add_u32 s28, s34, s26
	s_addc_u32 s29, s35, s27
	s_lshl_b64 s[28:29], s[28:29], 15
	s_add_u32 s30, s12, s28
	s_addc_u32 s31, s13, s29
	s_or_b32 s28, s26, 2
	s_ashr_i32 s29, s28, 31
	s_add_u32 s34, s34, s28
	v_lshlrev_b32_e32 v169, 7, v168
	s_addc_u32 s35, s35, s29
	v_and_b32_e32 v138, 0x6780, v169
	s_lshl_b64 s[34:35], s[34:35], 15
	v_mov_b32_e32 v91, v139
	v_lshlrev_b32_e32 v90, 1, v90
	v_lshl_add_u64 v[192:193], s[30:31], 0, v[138:139]
	s_add_u32 s34, s12, s34
	v_lshl_add_u64 v[192:193], v[192:193], 0, v[90:91]
	s_addc_u32 s35, s13, s35
	s_and_b64 vcc, exec, s[0:1]
	s_mov_b64 s[0:1], -1
	s_waitcnt vmcnt(0)
	v_pk_mul_f32 v[194:195], v[6:7], v[190:191] op_sel_hi:[1,0]
	v_pk_mul_f32 v[196:197], v[8:9], v[190:191] op_sel_hi:[1,0]
	v_pk_mul_f32 v[198:199], v[2:3], v[190:191] op_sel_hi:[1,0]
	v_pk_mul_f32 v[204:205], v[32:33], v[190:191] op_sel_hi:[1,0]
	v_pk_fma_f32 v[170:171], v[196:197], v[170:171], v[28:29]
	v_pk_fma_f32 v[172:173], v[194:195], v[172:173], v[26:27]
	v_pk_mul_f32 v[200:201], v[4:5], v[190:191] op_sel_hi:[1,0]
	v_pk_mul_f32 v[202:203], v[30:31], v[190:191] op_sel_hi:[1,0]
	v_pk_mul_f32 v[206:207], v[14:15], v[190:191] op_sel_hi:[1,0]
	v_pk_mul_f32 v[190:191], v[16:17], v[190:191] op_sel_hi:[1,0]
	v_pk_fma_f32 v[174:175], v[198:199], v[174:175], v[22:23]
	v_pk_fma_f32 v[182:183], v[204:205], v[182:183], v[20:21]
	v_max_f32_e32 v173, 0, v173
	v_max_f32_e32 v172, 0, v172
	v_max_f32_e32 v171, 0, v171
	v_max_f32_e32 v170, 0, v170
	v_pk_fma_f32 v[176:177], v[200:201], v[176:177], v[24:25]
	v_pk_fma_f32 v[180:181], v[202:203], v[180:181], v[18:19]
	v_pk_fma_f32 v[184:185], v[190:191], v[184:185], v[12:13]
	v_max_f32_e32 v175, 0, v175
	v_max_f32_e32 v174, 0, v174
	v_max_f32_e32 v183, 0, v183
	v_max_f32_e32 v182, 0, v182
	v_pk_mul_f32 v[190:191], v[170:171], v[170:171]
	v_pk_mul_f32 v[170:171], v[172:173], v[172:173]
	v_max_f32_e32 v177, 0, v177
	v_max_f32_e32 v176, 0, v176
	v_max_f32_e32 v181, 0, v181
	v_max_f32_e32 v180, 0, v180
	v_pk_mul_f32 v[172:173], v[174:175], v[174:175]
	v_pk_mul_f32 v[174:175], v[182:183], v[182:183]
	v_cvt_pk_bf16_f32 v170, v170, v171
	v_cvt_pk_bf16_f32 v171, v190, v191
	v_pk_fma_f32 v[178:179], v[206:207], v[178:179], v[10:11]
	v_pk_mul_f32 v[176:177], v[176:177], v[176:177]
	v_pk_mul_f32 v[180:181], v[180:181], v[180:181]
	v_cvt_pk_bf16_f32 v172, v172, v173
	v_cvt_pk_bf16_f32 v173, v176, v177
	global_store_dwordx4 v[192:193], v[170:173], off
	v_max_f32_e32 v179, 0, v179
	v_max_f32_e32 v178, 0, v178
	v_cvt_pk_bf16_f32 v170, v180, v181
	v_cvt_pk_bf16_f32 v171, v174, v175
	v_lshl_add_u64 v[174:175], s[34:35], 0, v[138:139]
	v_max_f32_e32 v185, 0, v185
	v_max_f32_e32 v184, 0, v184
	v_lshl_add_u64 v[174:175], v[174:175], 0, v[90:91]
	v_pk_mul_f32 v[182:183], v[184:185], v[184:185]
	v_pk_mul_f32 v[178:179], v[178:179], v[178:179]
	s_nop 0
	v_cvt_pk_bf16_f32 v172, v178, v179
	v_cvt_pk_bf16_f32 v173, v182, v183
	global_store_dwordx4 v[174:175], v[170:173], off
	v_or_b32_e32 v174, 32, v168
	v_ashrrev_i32_e32 v175, 31, v174
	v_or_b32_e32 v170, 16, v168
	v_ashrrev_i32_e32 v171, 31, v170
	v_lshl_add_u64 v[172:173], v[170:171], 2, s[14:15]
	s_nop 1
	v_mov_b32_e32 v172, v240
	v_lshlrev_b32_e32 v138, 7, v170
	v_and_b32_e32 v138, 0x6f80, v138
	v_lshl_add_u64 v[176:177], s[30:31], 0, v[138:139]
	v_lshl_add_u64 v[178:179], s[34:35], 0, v[138:139]
	v_lshl_add_u64 v[176:177], v[176:177], 0, v[90:91]
	v_lshl_add_u64 v[178:179], v[178:179], 0, v[90:91]
	v_lshl_add_u64 v[170:171], v[174:175], 2, s[14:15]
	v_lshlrev_b32_e32 v138, 7, v174
	v_and_b32_e32 v138, 0x7780, v138
	s_nop 0
	v_pk_mul_f32 v[180:181], v[6:7], v[172:173] op_sel_hi:[1,0]
	v_pk_mul_f32 v[182:183], v[8:9], v[172:173] op_sel_hi:[1,0]
	v_pk_mul_f32 v[184:185], v[2:3], v[172:173] op_sel_hi:[1,0]
	v_pk_mul_f32 v[190:191], v[4:5], v[172:173] op_sel_hi:[1,0]
	v_pk_fma_f32 v[154:155], v[182:183], v[154:155], v[28:29]
	v_pk_fma_f32 v[152:153], v[180:181], v[152:153], v[26:27]
	v_pk_mul_f32 v[192:193], v[30:31], v[172:173] op_sel_hi:[1,0]
	v_pk_mul_f32 v[194:195], v[32:33], v[172:173] op_sel_hi:[1,0]
	v_pk_mul_f32 v[196:197], v[14:15], v[172:173] op_sel_hi:[1,0]
	v_pk_mul_f32 v[172:173], v[16:17], v[172:173] op_sel_hi:[1,0]
	v_pk_fma_f32 v[158:159], v[190:191], v[158:159], v[24:25]
	v_pk_fma_f32 v[156:157], v[184:185], v[156:157], v[22:23]
	v_max_f32_e32 v153, 0, v153
	v_max_f32_e32 v152, 0, v152
	v_max_f32_e32 v155, 0, v155
	v_max_f32_e32 v154, 0, v154
	v_pk_fma_f32 v[162:163], v[194:195], v[162:163], v[20:21]
	v_pk_fma_f32 v[160:161], v[192:193], v[160:161], v[18:19]
	v_pk_fma_f32 v[166:167], v[172:173], v[166:167], v[12:13]
	v_pk_fma_f32 v[164:165], v[196:197], v[164:165], v[10:11]
	v_max_f32_e32 v157, 0, v157
	v_max_f32_e32 v156, 0, v156
	v_max_f32_e32 v159, 0, v159
	v_max_f32_e32 v158, 0, v158
	v_pk_mul_f32 v[154:155], v[154:155], v[154:155]
	v_pk_mul_f32 v[152:153], v[152:153], v[152:153]
	v_max_f32_e32 v161, 0, v161
	v_max_f32_e32 v160, 0, v160
	v_max_f32_e32 v163, 0, v163
	v_max_f32_e32 v162, 0, v162
	v_max_f32_e32 v165, 0, v165
	v_max_f32_e32 v164, 0, v164
	v_max_f32_e32 v167, 0, v167
	v_max_f32_e32 v166, 0, v166
	v_pk_mul_f32 v[158:159], v[158:159], v[158:159]
	v_pk_mul_f32 v[156:157], v[156:157], v[156:157]
	v_cvt_pk_bf16_f32 v152, v152, v153
	v_cvt_pk_bf16_f32 v153, v154, v155
	v_pk_mul_f32 v[162:163], v[162:163], v[162:163]
	v_cvt_pk_bf16_f32 v154, v156, v157
	v_cvt_pk_bf16_f32 v155, v158, v159
	v_pk_mul_f32 v[160:161], v[160:161], v[160:161]
	v_pk_mul_f32 v[166:167], v[166:167], v[166:167]
	v_pk_mul_f32 v[164:165], v[164:165], v[164:165]
	global_store_dwordx4 v[176:177], v[152:155], off
	v_lshl_add_u64 v[158:159], s[30:31], 0, v[138:139]
	v_lshl_add_u64 v[158:159], v[158:159], 0, v[90:91]
	v_cvt_pk_bf16_f32 v152, v160, v161
	v_cvt_pk_bf16_f32 v153, v162, v163
	v_cvt_pk_bf16_f32 v154, v164, v165
	v_cvt_pk_bf16_f32 v155, v166, v167
	global_store_dwordx4 v[178:179], v[152:155], off
	s_nop 1
	v_mov_b32_e32 v152, v241
	v_lshl_add_u64 v[160:161], s[34:35], 0, v[138:139]
	v_or_b32_e32 v154, 48, v168
	v_ashrrev_i32_e32 v155, 31, v154
	v_lshl_add_u64 v[160:161], v[160:161], 0, v[90:91]
	v_lshl_add_u64 v[156:157], v[154:155], 2, s[14:15]
	s_nop 0
	v_pk_mul_f32 v[162:163], v[6:7], v[152:153] op_sel_hi:[1,0]
	v_pk_mul_f32 v[164:165], v[8:9], v[152:153] op_sel_hi:[1,0]
	v_pk_mul_f32 v[166:167], v[2:3], v[152:153] op_sel_hi:[1,0]
	v_pk_mul_f32 v[170:171], v[4:5], v[152:153] op_sel_hi:[1,0]
	v_pk_fma_f32 v[120:121], v[164:165], v[120:121], v[28:29]
	v_pk_fma_f32 v[118:119], v[162:163], v[118:119], v[26:27]
	v_pk_mul_f32 v[172:173], v[30:31], v[152:153] op_sel_hi:[1,0]
	v_pk_mul_f32 v[174:175], v[32:33], v[152:153] op_sel_hi:[1,0]
	v_pk_mul_f32 v[176:177], v[14:15], v[152:153] op_sel_hi:[1,0]
	v_pk_mul_f32 v[152:153], v[16:17], v[152:153] op_sel_hi:[1,0]
	v_pk_fma_f32 v[124:125], v[170:171], v[124:125], v[24:25]
	v_pk_fma_f32 v[122:123], v[166:167], v[122:123], v[22:23]
	v_max_f32_e32 v119, 0, v119
	v_max_f32_e32 v118, 0, v118
	v_max_f32_e32 v121, 0, v121
	v_max_f32_e32 v120, 0, v120
	v_pk_fma_f32 v[128:129], v[174:175], v[128:129], v[20:21]
	v_pk_fma_f32 v[126:127], v[172:173], v[126:127], v[18:19]
	v_pk_fma_f32 v[150:151], v[152:153], v[150:151], v[12:13]
	v_pk_fma_f32 v[148:149], v[176:177], v[148:149], v[10:11]
	v_max_f32_e32 v123, 0, v123
	v_max_f32_e32 v122, 0, v122
	v_max_f32_e32 v125, 0, v125
	v_max_f32_e32 v124, 0, v124
	v_pk_mul_f32 v[120:121], v[120:121], v[120:121]
	v_pk_mul_f32 v[118:119], v[118:119], v[118:119]
	v_max_f32_e32 v127, 0, v127
	v_max_f32_e32 v126, 0, v126
	v_max_f32_e32 v129, 0, v129
	v_max_f32_e32 v128, 0, v128
	v_max_f32_e32 v149, 0, v149
	v_max_f32_e32 v148, 0, v148
	v_max_f32_e32 v151, 0, v151
	v_max_f32_e32 v150, 0, v150
	v_pk_mul_f32 v[124:125], v[124:125], v[124:125]
	v_pk_mul_f32 v[122:123], v[122:123], v[122:123]
	v_cvt_pk_bf16_f32 v118, v118, v119
	v_cvt_pk_bf16_f32 v119, v120, v121
	v_pk_mul_f32 v[128:129], v[128:129], v[128:129]
	v_cvt_pk_bf16_f32 v120, v122, v123
	v_cvt_pk_bf16_f32 v121, v124, v125
	v_pk_mul_f32 v[126:127], v[126:127], v[126:127]
	v_pk_mul_f32 v[150:151], v[150:151], v[150:151]
	v_pk_mul_f32 v[148:149], v[148:149], v[148:149]
	global_store_dwordx4 v[158:159], v[118:121], off
	s_nop 1
	v_cvt_pk_bf16_f32 v118, v126, v127
	v_cvt_pk_bf16_f32 v119, v128, v129
	v_cvt_pk_bf16_f32 v120, v148, v149
	v_cvt_pk_bf16_f32 v121, v150, v151
	global_store_dwordx4 v[160:161], v[118:121], off
	s_nop 1
	v_mov_b32_e32 v118, v242
	s_nop 0
	v_lshlrev_b32_e32 v119, 7, v154
	v_and_b32_e32 v138, 0x7f80, v119
	v_lshl_add_u64 v[120:121], s[30:31], 0, v[138:139]
	v_lshl_add_u64 v[122:123], s[34:35], 0, v[138:139]
	v_lshl_add_u64 v[120:121], v[120:121], 0, v[90:91]
	v_lshl_add_u64 v[122:123], v[122:123], 0, v[90:91]
	s_nop 0
	v_pk_mul_f32 v[124:125], v[6:7], v[118:119] op_sel_hi:[1,0]
	v_pk_mul_f32 v[126:127], v[8:9], v[118:119] op_sel_hi:[1,0]
	v_pk_mul_f32 v[128:129], v[2:3], v[118:119] op_sel_hi:[1,0]
	v_pk_mul_f32 v[148:149], v[4:5], v[118:119] op_sel_hi:[1,0]
	v_pk_fma_f32 v[104:105], v[126:127], v[104:105], v[28:29]
	v_pk_fma_f32 v[102:103], v[124:125], v[102:103], v[26:27]
	v_pk_mul_f32 v[150:151], v[30:31], v[118:119] op_sel_hi:[1,0]
	v_pk_mul_f32 v[152:153], v[32:33], v[118:119] op_sel_hi:[1,0]
	v_pk_mul_f32 v[154:155], v[14:15], v[118:119] op_sel_hi:[1,0]
	v_pk_mul_f32 v[118:119], v[16:17], v[118:119] op_sel_hi:[1,0]
	v_pk_fma_f32 v[108:109], v[148:149], v[108:109], v[24:25]
	v_pk_fma_f32 v[106:107], v[128:129], v[106:107], v[22:23]
	v_max_f32_e32 v103, 0, v103
	v_max_f32_e32 v102, 0, v102
	v_max_f32_e32 v105, 0, v105
	v_max_f32_e32 v104, 0, v104
	v_pk_fma_f32 v[112:113], v[152:153], v[112:113], v[20:21]
	v_pk_fma_f32 v[110:111], v[150:151], v[110:111], v[18:19]
	v_pk_fma_f32 v[116:117], v[118:119], v[116:117], v[12:13]
	v_pk_fma_f32 v[114:115], v[154:155], v[114:115], v[10:11]
	v_max_f32_e32 v107, 0, v107
	v_max_f32_e32 v106, 0, v106
	v_max_f32_e32 v109, 0, v109
	v_max_f32_e32 v108, 0, v108
	v_pk_mul_f32 v[104:105], v[104:105], v[104:105]
	v_pk_mul_f32 v[102:103], v[102:103], v[102:103]
	v_max_f32_e32 v111, 0, v111
	v_max_f32_e32 v110, 0, v110
	v_max_f32_e32 v113, 0, v113
	v_max_f32_e32 v112, 0, v112
	v_max_f32_e32 v115, 0, v115
	v_max_f32_e32 v114, 0, v114
	v_max_f32_e32 v117, 0, v117
	v_max_f32_e32 v116, 0, v116
	v_pk_mul_f32 v[108:109], v[108:109], v[108:109]
	v_pk_mul_f32 v[106:107], v[106:107], v[106:107]
	v_cvt_pk_bf16_f32 v102, v102, v103
	v_cvt_pk_bf16_f32 v103, v104, v105
	v_pk_mul_f32 v[112:113], v[112:113], v[112:113]
	v_cvt_pk_bf16_f32 v104, v106, v107
	v_cvt_pk_bf16_f32 v105, v108, v109
	v_pk_mul_f32 v[110:111], v[110:111], v[110:111]
	v_pk_mul_f32 v[116:117], v[116:117], v[116:117]
	v_pk_mul_f32 v[114:115], v[114:115], v[114:115]
	global_store_dwordx4 v[120:121], v[102:105], off
	s_nop 1
	v_cvt_pk_bf16_f32 v102, v110, v111
	v_cvt_pk_bf16_f32 v103, v112, v113
	v_cvt_pk_bf16_f32 v104, v114, v115
	v_cvt_pk_bf16_f32 v105, v116, v117
	global_store_dwordx4 v[122:123], v[102:105], off
	s_nop 1
	v_mov_b32_e32 v106, v243
	s_nop 0
	v_add_u32_e32 v103, 0x80, v168
	v_ashrrev_i32_e32 v102, 8, v103
	v_lshlrev_b32_e32 v107, 7, v103
	v_ashrrev_i32_e32 v103, 31, v102
	v_lshlrev_b64 v[104:105], 7, v[102:103]
	v_lshl_add_u64 v[102:103], v[104:105], 0, s[26:27]
	v_lshl_add_u64 v[104:105], v[104:105], 0, s[28:29]
	v_lshlrev_b64 v[102:103], 15, v[102:103]
	v_lshlrev_b64 v[104:105], 15, v[104:105]
	v_lshl_add_u64 v[102:103], s[12:13], 0, v[102:103]
	v_lshl_add_u64 v[104:105], s[12:13], 0, v[104:105]
	v_and_b32_e32 v138, 0x6780, v107
	v_lshl_add_u64 v[108:109], v[102:103], 0, v[138:139]
	v_lshl_add_u64 v[110:111], v[104:105], 0, v[138:139]
	v_lshl_add_u64 v[108:109], v[108:109], 0, v[90:91]
	v_lshl_add_u64 v[110:111], v[110:111], 0, v[90:91]
	s_nop 0
	v_pk_mul_f32 v[112:113], v[6:7], v[106:107] op_sel_hi:[1,0]
	v_pk_mul_f32 v[114:115], v[8:9], v[106:107] op_sel_hi:[1,0]
	v_pk_mul_f32 v[116:117], v[2:3], v[106:107] op_sel_hi:[1,0]
	v_pk_mul_f32 v[118:119], v[4:5], v[106:107] op_sel_hi:[1,0]
	v_pk_fma_f32 v[84:85], v[114:115], v[84:85], v[28:29]
	v_pk_fma_f32 v[82:83], v[112:113], v[82:83], v[26:27]
	v_pk_mul_f32 v[120:121], v[30:31], v[106:107] op_sel_hi:[1,0]
	v_pk_mul_f32 v[122:123], v[32:33], v[106:107] op_sel_hi:[1,0]
	v_pk_mul_f32 v[124:125], v[14:15], v[106:107] op_sel_hi:[1,0]
	v_pk_mul_f32 v[106:107], v[16:17], v[106:107] op_sel_hi:[1,0]
	v_pk_fma_f32 v[88:89], v[118:119], v[88:89], v[24:25]
	v_pk_fma_f32 v[86:87], v[116:117], v[86:87], v[22:23]
	v_max_f32_e32 v83, 0, v83
	v_max_f32_e32 v82, 0, v82
	v_max_f32_e32 v85, 0, v85
	v_max_f32_e32 v84, 0, v84
	v_pk_fma_f32 v[94:95], v[122:123], v[94:95], v[20:21]
	v_pk_fma_f32 v[92:93], v[120:121], v[92:93], v[18:19]
	v_pk_fma_f32 v[98:99], v[106:107], v[98:99], v[12:13]
	v_pk_fma_f32 v[96:97], v[124:125], v[96:97], v[10:11]
	v_max_f32_e32 v87, 0, v87
	v_max_f32_e32 v86, 0, v86
	v_max_f32_e32 v89, 0, v89
	v_max_f32_e32 v88, 0, v88
	v_pk_mul_f32 v[84:85], v[84:85], v[84:85]
	v_pk_mul_f32 v[82:83], v[82:83], v[82:83]
	v_max_f32_e32 v93, 0, v93
	v_max_f32_e32 v92, 0, v92
	v_max_f32_e32 v95, 0, v95
	v_max_f32_e32 v94, 0, v94
	v_max_f32_e32 v97, 0, v97
	v_max_f32_e32 v96, 0, v96
	v_max_f32_e32 v99, 0, v99
	v_max_f32_e32 v98, 0, v98
	v_pk_mul_f32 v[88:89], v[88:89], v[88:89]
	v_pk_mul_f32 v[86:87], v[86:87], v[86:87]
	v_cvt_pk_bf16_f32 v82, v82, v83
	v_cvt_pk_bf16_f32 v83, v84, v85
	v_pk_mul_f32 v[94:95], v[94:95], v[94:95]
	v_cvt_pk_bf16_f32 v84, v86, v87
	v_cvt_pk_bf16_f32 v85, v88, v89
	v_pk_mul_f32 v[92:93], v[92:93], v[92:93]
	v_pk_mul_f32 v[98:99], v[98:99], v[98:99]
	v_pk_mul_f32 v[96:97], v[96:97], v[96:97]
	global_store_dwordx4 v[108:109], v[82:85], off
	s_nop 1
	v_cvt_pk_bf16_f32 v82, v92, v93
	v_cvt_pk_bf16_f32 v83, v94, v95
	v_cvt_pk_bf16_f32 v84, v96, v97
	v_cvt_pk_bf16_f32 v85, v98, v99
	global_store_dwordx4 v[110:111], v[82:85], off
	s_nop 1
	v_mov_b32_e32 v82, v244
	s_nop 0
	v_add_u32_e32 v83, 0x4800, v169
	v_and_b32_e32 v138, 0x6f80, v83
	v_lshl_add_u64 v[84:85], v[102:103], 0, v[138:139]
	v_lshl_add_u64 v[86:87], v[104:105], 0, v[138:139]
	v_lshl_add_u64 v[84:85], v[84:85], 0, v[90:91]
	v_lshl_add_u64 v[86:87], v[86:87], 0, v[90:91]
	s_nop 0
	v_pk_mul_f32 v[88:89], v[6:7], v[82:83] op_sel_hi:[1,0]
	v_pk_mul_f32 v[92:93], v[8:9], v[82:83] op_sel_hi:[1,0]
	v_pk_mul_f32 v[94:95], v[2:3], v[82:83] op_sel_hi:[1,0]
	v_pk_mul_f32 v[96:97], v[4:5], v[82:83] op_sel_hi:[1,0]
	v_pk_fma_f32 v[68:69], v[92:93], v[68:69], v[28:29]
	v_pk_fma_f32 v[66:67], v[88:89], v[66:67], v[26:27]
	v_pk_mul_f32 v[98:99], v[30:31], v[82:83] op_sel_hi:[1,0]
	v_pk_mul_f32 v[106:107], v[32:33], v[82:83] op_sel_hi:[1,0]
	v_pk_mul_f32 v[108:109], v[14:15], v[82:83] op_sel_hi:[1,0]
	v_pk_mul_f32 v[82:83], v[16:17], v[82:83] op_sel_hi:[1,0]
	v_pk_fma_f32 v[72:73], v[96:97], v[72:73], v[24:25]
	v_pk_fma_f32 v[70:71], v[94:95], v[70:71], v[22:23]
	v_max_f32_e32 v67, 0, v67
	v_max_f32_e32 v66, 0, v66
	v_max_f32_e32 v69, 0, v69
	v_max_f32_e32 v68, 0, v68
	v_pk_fma_f32 v[76:77], v[106:107], v[76:77], v[20:21]
	v_pk_fma_f32 v[74:75], v[98:99], v[74:75], v[18:19]
	v_pk_fma_f32 v[80:81], v[82:83], v[80:81], v[12:13]
	v_pk_fma_f32 v[78:79], v[108:109], v[78:79], v[10:11]
	v_max_f32_e32 v71, 0, v71
	v_max_f32_e32 v70, 0, v70
	v_max_f32_e32 v73, 0, v73
	v_max_f32_e32 v72, 0, v72
	v_pk_mul_f32 v[68:69], v[68:69], v[68:69]
	v_pk_mul_f32 v[66:67], v[66:67], v[66:67]
	v_max_f32_e32 v75, 0, v75
	v_max_f32_e32 v74, 0, v74
	v_max_f32_e32 v77, 0, v77
	v_max_f32_e32 v76, 0, v76
	v_max_f32_e32 v79, 0, v79
	v_max_f32_e32 v78, 0, v78
	v_max_f32_e32 v81, 0, v81
	v_max_f32_e32 v80, 0, v80
	v_pk_mul_f32 v[72:73], v[72:73], v[72:73]
	v_pk_mul_f32 v[70:71], v[70:71], v[70:71]
	v_cvt_pk_bf16_f32 v66, v66, v67
	v_cvt_pk_bf16_f32 v67, v68, v69
	v_pk_mul_f32 v[76:77], v[76:77], v[76:77]
	v_cvt_pk_bf16_f32 v68, v70, v71
	v_cvt_pk_bf16_f32 v69, v72, v73
	v_pk_mul_f32 v[74:75], v[74:75], v[74:75]
	v_pk_mul_f32 v[80:81], v[80:81], v[80:81]
	v_pk_mul_f32 v[78:79], v[78:79], v[78:79]
	global_store_dwordx4 v[84:85], v[66:69], off
	s_nop 1
	v_cvt_pk_bf16_f32 v66, v74, v75
	v_cvt_pk_bf16_f32 v67, v76, v77
	v_cvt_pk_bf16_f32 v68, v78, v79
	v_cvt_pk_bf16_f32 v69, v80, v81
	global_store_dwordx4 v[86:87], v[66:69], off
	s_nop 1
	v_mov_b32_e32 v66, v245
	s_nop 0
	v_add_u32_e32 v67, 0x5000, v169
	v_and_b32_e32 v138, 0x7780, v67
	v_lshl_add_u64 v[68:69], v[102:103], 0, v[138:139]
	v_lshl_add_u64 v[70:71], v[104:105], 0, v[138:139]
	v_lshl_add_u64 v[68:69], v[68:69], 0, v[90:91]
	v_lshl_add_u64 v[70:71], v[70:71], 0, v[90:91]
	s_nop 0
	v_pk_mul_f32 v[72:73], v[6:7], v[66:67] op_sel_hi:[1,0]
	v_pk_mul_f32 v[74:75], v[8:9], v[66:67] op_sel_hi:[1,0]
	v_pk_mul_f32 v[76:77], v[2:3], v[66:67] op_sel_hi:[1,0]
	v_pk_mul_f32 v[78:79], v[4:5], v[66:67] op_sel_hi:[1,0]
	v_pk_fma_f32 v[52:53], v[74:75], v[52:53], v[28:29]
	v_pk_fma_f32 v[50:51], v[72:73], v[50:51], v[26:27]
	v_pk_mul_f32 v[80:81], v[30:31], v[66:67] op_sel_hi:[1,0]
	v_pk_mul_f32 v[82:83], v[32:33], v[66:67] op_sel_hi:[1,0]
	v_pk_mul_f32 v[84:85], v[14:15], v[66:67] op_sel_hi:[1,0]
	v_pk_mul_f32 v[66:67], v[16:17], v[66:67] op_sel_hi:[1,0]
	v_pk_fma_f32 v[56:57], v[78:79], v[56:57], v[24:25]
	v_pk_fma_f32 v[54:55], v[76:77], v[54:55], v[22:23]
	v_max_f32_e32 v51, 0, v51
	v_max_f32_e32 v50, 0, v50
	v_max_f32_e32 v53, 0, v53
	v_max_f32_e32 v52, 0, v52
	v_pk_fma_f32 v[60:61], v[82:83], v[60:61], v[20:21]
	v_pk_fma_f32 v[58:59], v[80:81], v[58:59], v[18:19]
	v_pk_fma_f32 v[64:65], v[66:67], v[64:65], v[12:13]
	v_pk_fma_f32 v[62:63], v[84:85], v[62:63], v[10:11]
	v_max_f32_e32 v55, 0, v55
	v_max_f32_e32 v54, 0, v54
	v_max_f32_e32 v57, 0, v57
	v_max_f32_e32 v56, 0, v56
	v_pk_mul_f32 v[52:53], v[52:53], v[52:53]
	v_pk_mul_f32 v[50:51], v[50:51], v[50:51]
	v_max_f32_e32 v59, 0, v59
	v_max_f32_e32 v58, 0, v58
	v_max_f32_e32 v61, 0, v61
	v_max_f32_e32 v60, 0, v60
	v_max_f32_e32 v63, 0, v63
	v_max_f32_e32 v62, 0, v62
	v_max_f32_e32 v65, 0, v65
	v_max_f32_e32 v64, 0, v64
	v_pk_mul_f32 v[56:57], v[56:57], v[56:57]
	v_pk_mul_f32 v[54:55], v[54:55], v[54:55]
	v_cvt_pk_bf16_f32 v50, v50, v51
	v_cvt_pk_bf16_f32 v51, v52, v53
	v_pk_mul_f32 v[60:61], v[60:61], v[60:61]
	v_cvt_pk_bf16_f32 v52, v54, v55
	v_cvt_pk_bf16_f32 v53, v56, v57
	v_pk_mul_f32 v[58:59], v[58:59], v[58:59]
	v_pk_mul_f32 v[64:65], v[64:65], v[64:65]
	v_pk_mul_f32 v[62:63], v[62:63], v[62:63]
	global_store_dwordx4 v[68:69], v[50:53], off
	s_nop 1
	v_cvt_pk_bf16_f32 v50, v58, v59
	v_cvt_pk_bf16_f32 v51, v60, v61
	v_cvt_pk_bf16_f32 v52, v62, v63
	v_cvt_pk_bf16_f32 v53, v64, v65
	global_store_dwordx4 v[70:71], v[50:53], off
	s_nop 1
	v_mov_b32_e32 v50, v246
	s_nop 0
	v_add_u32_e32 v51, 0x5800, v169
	v_and_b32_e32 v138, 0x7f80, v51
	v_lshl_add_u64 v[52:53], v[102:103], 0, v[138:139]
	v_lshl_add_u64 v[54:55], v[104:105], 0, v[138:139]
	v_lshl_add_u64 v[52:53], v[52:53], 0, v[90:91]
	v_lshl_add_u64 v[54:55], v[54:55], 0, v[90:91]
	s_nop 0
	v_pk_mul_f32 v[2:3], v[2:3], v[50:51] op_sel_hi:[1,0]
	v_pk_mul_f32 v[4:5], v[4:5], v[50:51] op_sel_hi:[1,0]
	v_pk_mul_f32 v[6:7], v[6:7], v[50:51] op_sel_hi:[1,0]
	v_pk_mul_f32 v[8:9], v[8:9], v[50:51] op_sel_hi:[1,0]
	v_pk_mul_f32 v[30:31], v[30:31], v[50:51] op_sel_hi:[1,0]
	v_pk_fma_f32 v[4:5], v[4:5], v[40:41], v[24:25]
	v_pk_fma_f32 v[2:3], v[2:3], v[38:39], v[22:23]
	v_pk_mul_f32 v[32:33], v[32:33], v[50:51] op_sel_hi:[1,0]
	v_pk_mul_f32 v[14:15], v[14:15], v[50:51] op_sel_hi:[1,0]
	v_pk_mul_f32 v[16:17], v[16:17], v[50:51] op_sel_hi:[1,0]
	v_pk_fma_f32 v[8:9], v[8:9], v[36:37], v[28:29]
	v_pk_fma_f32 v[6:7], v[6:7], v[34:35], v[26:27]
	v_pk_fma_f32 v[18:19], v[30:31], v[42:43], v[18:19]
	v_max_f32_e32 v3, 0, v3
	v_max_f32_e32 v2, 0, v2
	v_max_f32_e32 v5, 0, v5
	v_max_f32_e32 v4, 0, v4
	v_pk_fma_f32 v[20:21], v[32:33], v[44:45], v[20:21]
	v_pk_fma_f32 v[12:13], v[16:17], v[48:49], v[12:13]
	v_pk_fma_f32 v[10:11], v[14:15], v[46:47], v[10:11]
	v_max_f32_e32 v7, 0, v7
	v_max_f32_e32 v6, 0, v6
	v_max_f32_e32 v9, 0, v9
	v_max_f32_e32 v8, 0, v8
	v_max_f32_e32 v15, 0, v19
	v_max_f32_e32 v14, 0, v18
	v_pk_mul_f32 v[18:19], v[4:5], v[4:5]
	v_pk_mul_f32 v[4:5], v[2:3], v[2:3]
	v_max_f32_e32 v17, 0, v21
	v_max_f32_e32 v16, 0, v20
	v_max_f32_e32 v11, 0, v11
	v_max_f32_e32 v10, 0, v10
	v_max_f32_e32 v13, 0, v13
	v_max_f32_e32 v12, 0, v12
	v_pk_mul_f32 v[8:9], v[8:9], v[8:9]
	v_pk_mul_f32 v[6:7], v[6:7], v[6:7]
	v_pk_mul_f32 v[16:17], v[16:17], v[16:17]
	v_cvt_pk_bf16_f32 v2, v6, v7
	v_cvt_pk_bf16_f32 v3, v8, v9
	v_cvt_pk_bf16_f32 v4, v4, v5
	v_cvt_pk_bf16_f32 v5, v18, v19
	v_pk_mul_f32 v[14:15], v[14:15], v[14:15]
	v_pk_mul_f32 v[12:13], v[12:13], v[12:13]
	v_pk_mul_f32 v[10:11], v[10:11], v[10:11]
	global_store_dwordx4 v[52:53], v[2:5], off
	s_nop 1
	v_cvt_pk_bf16_f32 v2, v14, v15
	v_cvt_pk_bf16_f32 v3, v16, v17
	v_cvt_pk_bf16_f32 v4, v10, v11
	v_cvt_pk_bf16_f32 v5, v12, v13
	global_store_dwordx4 v[54:55], v[2:5], off
	s_cbranch_vccnz .LBB0_2936
	s_andn2_b64 vcc, exec, s[10:11]
	s_cbranch_vccnz .LBB0_2935
	s_barrier
	s_branch .LBB0_2935

.LBB0_3802:
	s_lshl_b32 s26, s30, 8
	s_add_i32 s28, s26, s52
	s_lshl_b32 s26, s31, 8
	s_or_b32 s29, s26, s53
	s_lshr_b32 s26, s30, 4
	s_add_i32 s26, s26, -1
	v_or_b32_e32 v2, s29, v186
	s_cmp_gt_i32 s30, 31
	s_cselect_b32 s26, s26, 0
	v_ashrrev_i32_e32 v3, 31, v2
	v_or_b32_e32 v168, s28, v187
	v_lshlrev_b64 v[10:11], 2, v[2:3]
	v_ashrrev_i32_e32 v169, 31, v168
	s_ashr_i32 s27, s26, 31
	v_lshl_add_u64 v[12:13], s[16:17], 0, v[10:11]
	v_lshl_add_u64 v[100:101], v[168:169], 2, s[14:15]
	s_lshl_b64 s[26:27], s[26:27], 15
	global_load_dwordx4 v[2:5], v[12:13], off offset:16
	global_load_dwordx4 v[6:9], v[12:13], off
	global_load_dword v190, v[100:101], off
	global_load_dword v240, v[100:101], off offset:64
	global_load_dword v241, v[100:101], off offset:128
	global_load_dword v242, v[100:101], off offset:192
	global_load_dword v243, v[100:101], off offset:512
	global_load_dword v244, v[100:101], off offset:576
	global_load_dword v245, v[100:101], off offset:640
	global_load_dword v246, v[100:101], off offset:704
	s_add_u32 s26, s47, s26
	global_load_dwordx4 v[14:17], v[12:13], off offset:528
	global_load_dwordx4 v[30:33], v[12:13], off offset:512
	s_addc_u32 s27, s48, s27
	v_lshl_add_u64 v[10:11], s[26:27], 0, v[10:11]
	global_load_dwordx4 v[26:29], v[10:11], off
	global_load_dwordx4 v[22:25], v[10:11], off offset:16
	global_load_dwordx4 v[18:21], v[10:11], off offset:512
	s_nop 0
	global_load_dwordx4 v[10:13], v[10:11], off offset:528
	s_ashr_i32 s28, s28, 8
	v_bitop3_b32 v90, s29, 56, v186 bitop3:0xc8
	s_ashr_i32 s26, s29, 6
	s_ashr_i32 s29, s28, 31
	s_ashr_i32 s27, s26, 31
	s_lshl_b64 s[34:35], s[28:29], 7
	s_add_u32 s28, s34, s26
	s_addc_u32 s29, s35, s27
	s_lshl_b64 s[28:29], s[28:29], 15
	s_add_u32 s30, s12, s28
	s_addc_u32 s31, s13, s29
	s_or_b32 s28, s26, 2
	s_ashr_i32 s29, s28, 31
	s_add_u32 s34, s34, s28
	v_lshlrev_b32_e32 v169, 7, v168
	s_addc_u32 s35, s35, s29
	v_and_b32_e32 v138, 0x6780, v169
	s_lshl_b64 s[34:35], s[34:35], 15
	v_mov_b32_e32 v91, v139
	v_lshlrev_b32_e32 v90, 1, v90
	v_lshl_add_u64 v[192:193], s[30:31], 0, v[138:139]
	s_add_u32 s34, s12, s34
	v_lshl_add_u64 v[192:193], v[192:193], 0, v[90:91]
	s_addc_u32 s35, s13, s35
	s_and_b64 vcc, exec, s[0:1]
	s_mov_b64 s[0:1], -1
	s_waitcnt vmcnt(0)
	v_pk_mul_f32 v[194:195], v[6:7], v[190:191] op_sel_hi:[1,0]
	v_pk_mul_f32 v[196:197], v[8:9], v[190:191] op_sel_hi:[1,0]
	v_pk_mul_f32 v[198:199], v[2:3], v[190:191] op_sel_hi:[1,0]
	v_pk_mul_f32 v[204:205], v[32:33], v[190:191] op_sel_hi:[1,0]
	v_pk_fma_f32 v[170:171], v[196:197], v[170:171], v[28:29]
	v_pk_fma_f32 v[172:173], v[194:195], v[172:173], v[26:27]
	v_pk_mul_f32 v[200:201], v[4:5], v[190:191] op_sel_hi:[1,0]
	v_pk_mul_f32 v[202:203], v[30:31], v[190:191] op_sel_hi:[1,0]
	v_pk_mul_f32 v[206:207], v[14:15], v[190:191] op_sel_hi:[1,0]
	v_pk_mul_f32 v[190:191], v[16:17], v[190:191] op_sel_hi:[1,0]
	v_pk_fma_f32 v[174:175], v[198:199], v[174:175], v[22:23]
	v_pk_fma_f32 v[182:183], v[204:205], v[182:183], v[20:21]
	v_max_f32_e32 v173, 0, v173
	v_max_f32_e32 v172, 0, v172
	v_max_f32_e32 v171, 0, v171
	v_max_f32_e32 v170, 0, v170
	v_pk_fma_f32 v[176:177], v[200:201], v[176:177], v[24:25]
	v_pk_fma_f32 v[180:181], v[202:203], v[180:181], v[18:19]
	v_pk_fma_f32 v[184:185], v[190:191], v[184:185], v[12:13]
	v_max_f32_e32 v175, 0, v175
	v_max_f32_e32 v174, 0, v174
	v_max_f32_e32 v183, 0, v183
	v_max_f32_e32 v182, 0, v182
	v_pk_mul_f32 v[190:191], v[170:171], v[170:171]
	v_pk_mul_f32 v[170:171], v[172:173], v[172:173]
	v_max_f32_e32 v177, 0, v177
	v_max_f32_e32 v176, 0, v176
	v_max_f32_e32 v181, 0, v181
	v_max_f32_e32 v180, 0, v180
	v_pk_mul_f32 v[172:173], v[174:175], v[174:175]
	v_pk_mul_f32 v[174:175], v[182:183], v[182:183]
	v_cvt_pk_bf16_f32 v170, v170, v171
	v_cvt_pk_bf16_f32 v171, v190, v191
	v_pk_fma_f32 v[178:179], v[206:207], v[178:179], v[10:11]
	v_pk_mul_f32 v[176:177], v[176:177], v[176:177]
	v_pk_mul_f32 v[180:181], v[180:181], v[180:181]
	v_cvt_pk_bf16_f32 v172, v172, v173
	v_cvt_pk_bf16_f32 v173, v176, v177
	global_store_dwordx4 v[192:193], v[170:173], off
	v_max_f32_e32 v179, 0, v179
	v_max_f32_e32 v178, 0, v178
	v_cvt_pk_bf16_f32 v170, v180, v181
	v_cvt_pk_bf16_f32 v171, v174, v175
	v_lshl_add_u64 v[174:175], s[34:35], 0, v[138:139]
	v_max_f32_e32 v185, 0, v185
	v_max_f32_e32 v184, 0, v184
	v_lshl_add_u64 v[174:175], v[174:175], 0, v[90:91]
	v_pk_mul_f32 v[182:183], v[184:185], v[184:185]
	v_pk_mul_f32 v[178:179], v[178:179], v[178:179]
	s_nop 0
	v_cvt_pk_bf16_f32 v172, v178, v179
	v_cvt_pk_bf16_f32 v173, v182, v183
	global_store_dwordx4 v[174:175], v[170:173], off
	v_or_b32_e32 v174, 32, v168
	v_ashrrev_i32_e32 v175, 31, v174
	v_or_b32_e32 v170, 16, v168
	v_ashrrev_i32_e32 v171, 31, v170
	v_lshl_add_u64 v[172:173], v[170:171], 2, s[14:15]
	s_nop 1
	v_mov_b32_e32 v172, v240
	v_lshlrev_b32_e32 v138, 7, v170
	v_and_b32_e32 v138, 0x6f80, v138
	v_lshl_add_u64 v[176:177], s[30:31], 0, v[138:139]
	v_lshl_add_u64 v[178:179], s[34:35], 0, v[138:139]
	v_lshl_add_u64 v[176:177], v[176:177], 0, v[90:91]
	v_lshl_add_u64 v[178:179], v[178:179], 0, v[90:91]
	v_lshl_add_u64 v[170:171], v[174:175], 2, s[14:15]
	v_lshlrev_b32_e32 v138, 7, v174
	v_and_b32_e32 v138, 0x7780, v138
	s_nop 0
	v_pk_mul_f32 v[180:181], v[6:7], v[172:173] op_sel_hi:[1,0]
	v_pk_mul_f32 v[182:183], v[8:9], v[172:173] op_sel_hi:[1,0]
	v_pk_mul_f32 v[184:185], v[2:3], v[172:173] op_sel_hi:[1,0]
	v_pk_mul_f32 v[190:191], v[4:5], v[172:173] op_sel_hi:[1,0]
	v_pk_fma_f32 v[154:155], v[182:183], v[154:155], v[28:29]
	v_pk_fma_f32 v[152:153], v[180:181], v[152:153], v[26:27]
	v_pk_mul_f32 v[192:193], v[30:31], v[172:173] op_sel_hi:[1,0]
	v_pk_mul_f32 v[194:195], v[32:33], v[172:173] op_sel_hi:[1,0]
	v_pk_mul_f32 v[196:197], v[14:15], v[172:173] op_sel_hi:[1,0]
	v_pk_mul_f32 v[172:173], v[16:17], v[172:173] op_sel_hi:[1,0]
	v_pk_fma_f32 v[158:159], v[190:191], v[158:159], v[24:25]
	v_pk_fma_f32 v[156:157], v[184:185], v[156:157], v[22:23]
	v_max_f32_e32 v153, 0, v153
	v_max_f32_e32 v152, 0, v152
	v_max_f32_e32 v155, 0, v155
	v_max_f32_e32 v154, 0, v154
	v_pk_fma_f32 v[162:163], v[194:195], v[162:163], v[20:21]
	v_pk_fma_f32 v[160:161], v[192:193], v[160:161], v[18:19]
	v_pk_fma_f32 v[166:167], v[172:173], v[166:167], v[12:13]
	v_pk_fma_f32 v[164:165], v[196:197], v[164:165], v[10:11]
	v_max_f32_e32 v157, 0, v157
	v_max_f32_e32 v156, 0, v156
	v_max_f32_e32 v159, 0, v159
	v_max_f32_e32 v158, 0, v158
	v_pk_mul_f32 v[154:155], v[154:155], v[154:155]
	v_pk_mul_f32 v[152:153], v[152:153], v[152:153]
	v_max_f32_e32 v161, 0, v161
	v_max_f32_e32 v160, 0, v160
	v_max_f32_e32 v163, 0, v163
	v_max_f32_e32 v162, 0, v162
	v_max_f32_e32 v165, 0, v165
	v_max_f32_e32 v164, 0, v164
	v_max_f32_e32 v167, 0, v167
	v_max_f32_e32 v166, 0, v166
	v_pk_mul_f32 v[158:159], v[158:159], v[158:159]
	v_pk_mul_f32 v[156:157], v[156:157], v[156:157]
	v_cvt_pk_bf16_f32 v152, v152, v153
	v_cvt_pk_bf16_f32 v153, v154, v155
	v_pk_mul_f32 v[162:163], v[162:163], v[162:163]
	v_cvt_pk_bf16_f32 v154, v156, v157
	v_cvt_pk_bf16_f32 v155, v158, v159
	v_pk_mul_f32 v[160:161], v[160:161], v[160:161]
	v_pk_mul_f32 v[166:167], v[166:167], v[166:167]
	v_pk_mul_f32 v[164:165], v[164:165], v[164:165]
	global_store_dwordx4 v[176:177], v[152:155], off
	v_lshl_add_u64 v[158:159], s[30:31], 0, v[138:139]
	v_lshl_add_u64 v[158:159], v[158:159], 0, v[90:91]
	v_cvt_pk_bf16_f32 v152, v160, v161
	v_cvt_pk_bf16_f32 v153, v162, v163
	v_cvt_pk_bf16_f32 v154, v164, v165
	v_cvt_pk_bf16_f32 v155, v166, v167
	global_store_dwordx4 v[178:179], v[152:155], off
	s_nop 1
	v_mov_b32_e32 v152, v241
	v_lshl_add_u64 v[160:161], s[34:35], 0, v[138:139]
	v_or_b32_e32 v154, 48, v168
	v_ashrrev_i32_e32 v155, 31, v154
	v_lshl_add_u64 v[160:161], v[160:161], 0, v[90:91]
	v_lshl_add_u64 v[156:157], v[154:155], 2, s[14:15]
	s_nop 0
	v_pk_mul_f32 v[162:163], v[6:7], v[152:153] op_sel_hi:[1,0]
	v_pk_mul_f32 v[164:165], v[8:9], v[152:153] op_sel_hi:[1,0]
	v_pk_mul_f32 v[166:167], v[2:3], v[152:153] op_sel_hi:[1,0]
	v_pk_mul_f32 v[170:171], v[4:5], v[152:153] op_sel_hi:[1,0]
	v_pk_fma_f32 v[120:121], v[164:165], v[120:121], v[28:29]
	v_pk_fma_f32 v[118:119], v[162:163], v[118:119], v[26:27]
	v_pk_mul_f32 v[172:173], v[30:31], v[152:153] op_sel_hi:[1,0]
	v_pk_mul_f32 v[174:175], v[32:33], v[152:153] op_sel_hi:[1,0]
	v_pk_mul_f32 v[176:177], v[14:15], v[152:153] op_sel_hi:[1,0]
	v_pk_mul_f32 v[152:153], v[16:17], v[152:153] op_sel_hi:[1,0]
	v_pk_fma_f32 v[124:125], v[170:171], v[124:125], v[24:25]
	v_pk_fma_f32 v[122:123], v[166:167], v[122:123], v[22:23]
	v_max_f32_e32 v119, 0, v119
	v_max_f32_e32 v118, 0, v118
	v_max_f32_e32 v121, 0, v121
	v_max_f32_e32 v120, 0, v120
	v_pk_fma_f32 v[128:129], v[174:175], v[128:129], v[20:21]
	v_pk_fma_f32 v[126:127], v[172:173], v[126:127], v[18:19]
	v_pk_fma_f32 v[150:151], v[152:153], v[150:151], v[12:13]
	v_pk_fma_f32 v[148:149], v[176:177], v[148:149], v[10:11]
	v_max_f32_e32 v123, 0, v123
	v_max_f32_e32 v122, 0, v122
	v_max_f32_e32 v125, 0, v125
	v_max_f32_e32 v124, 0, v124
	v_pk_mul_f32 v[120:121], v[120:121], v[120:121]
	v_pk_mul_f32 v[118:119], v[118:119], v[118:119]
	v_max_f32_e32 v127, 0, v127
	v_max_f32_e32 v126, 0, v126
	v_max_f32_e32 v129, 0, v129
	v_max_f32_e32 v128, 0, v128
	v_max_f32_e32 v149, 0, v149
	v_max_f32_e32 v148, 0, v148
	v_max_f32_e32 v151, 0, v151
	v_max_f32_e32 v150, 0, v150
	v_pk_mul_f32 v[124:125], v[124:125], v[124:125]
	v_pk_mul_f32 v[122:123], v[122:123], v[122:123]
	v_cvt_pk_bf16_f32 v118, v118, v119
	v_cvt_pk_bf16_f32 v119, v120, v121
	v_pk_mul_f32 v[128:129], v[128:129], v[128:129]
	v_cvt_pk_bf16_f32 v120, v122, v123
	v_cvt_pk_bf16_f32 v121, v124, v125
	v_pk_mul_f32 v[126:127], v[126:127], v[126:127]
	v_pk_mul_f32 v[150:151], v[150:151], v[150:151]
	v_pk_mul_f32 v[148:149], v[148:149], v[148:149]
	global_store_dwordx4 v[158:159], v[118:121], off
	s_nop 1
	v_cvt_pk_bf16_f32 v118, v126, v127
	v_cvt_pk_bf16_f32 v119, v128, v129
	v_cvt_pk_bf16_f32 v120, v148, v149
	v_cvt_pk_bf16_f32 v121, v150, v151
	global_store_dwordx4 v[160:161], v[118:121], off
	s_nop 1
	v_mov_b32_e32 v118, v242
	s_nop 0
	v_lshlrev_b32_e32 v119, 7, v154
	v_and_b32_e32 v138, 0x7f80, v119
	v_lshl_add_u64 v[120:121], s[30:31], 0, v[138:139]
	v_lshl_add_u64 v[122:123], s[34:35], 0, v[138:139]
	v_lshl_add_u64 v[120:121], v[120:121], 0, v[90:91]
	v_lshl_add_u64 v[122:123], v[122:123], 0, v[90:91]
	s_nop 0
	v_pk_mul_f32 v[124:125], v[6:7], v[118:119] op_sel_hi:[1,0]
	v_pk_mul_f32 v[126:127], v[8:9], v[118:119] op_sel_hi:[1,0]
	v_pk_mul_f32 v[128:129], v[2:3], v[118:119] op_sel_hi:[1,0]
	v_pk_mul_f32 v[148:149], v[4:5], v[118:119] op_sel_hi:[1,0]
	v_pk_fma_f32 v[104:105], v[126:127], v[104:105], v[28:29]
	v_pk_fma_f32 v[102:103], v[124:125], v[102:103], v[26:27]
	v_pk_mul_f32 v[150:151], v[30:31], v[118:119] op_sel_hi:[1,0]
	v_pk_mul_f32 v[152:153], v[32:33], v[118:119] op_sel_hi:[1,0]
	v_pk_mul_f32 v[154:155], v[14:15], v[118:119] op_sel_hi:[1,0]
	v_pk_mul_f32 v[118:119], v[16:17], v[118:119] op_sel_hi:[1,0]
	v_pk_fma_f32 v[108:109], v[148:149], v[108:109], v[24:25]
	v_pk_fma_f32 v[106:107], v[128:129], v[106:107], v[22:23]
	v_max_f32_e32 v103, 0, v103
	v_max_f32_e32 v102, 0, v102
	v_max_f32_e32 v105, 0, v105
	v_max_f32_e32 v104, 0, v104
	v_pk_fma_f32 v[112:113], v[152:153], v[112:113], v[20:21]
	v_pk_fma_f32 v[110:111], v[150:151], v[110:111], v[18:19]
	v_pk_fma_f32 v[116:117], v[118:119], v[116:117], v[12:13]
	v_pk_fma_f32 v[114:115], v[154:155], v[114:115], v[10:11]
	v_max_f32_e32 v107, 0, v107
	v_max_f32_e32 v106, 0, v106
	v_max_f32_e32 v109, 0, v109
	v_max_f32_e32 v108, 0, v108
	v_pk_mul_f32 v[104:105], v[104:105], v[104:105]
	v_pk_mul_f32 v[102:103], v[102:103], v[102:103]
	v_max_f32_e32 v111, 0, v111
	v_max_f32_e32 v110, 0, v110
	v_max_f32_e32 v113, 0, v113
	v_max_f32_e32 v112, 0, v112
	v_max_f32_e32 v115, 0, v115
	v_max_f32_e32 v114, 0, v114
	v_max_f32_e32 v117, 0, v117
	v_max_f32_e32 v116, 0, v116
	v_pk_mul_f32 v[108:109], v[108:109], v[108:109]
	v_pk_mul_f32 v[106:107], v[106:107], v[106:107]
	v_cvt_pk_bf16_f32 v102, v102, v103
	v_cvt_pk_bf16_f32 v103, v104, v105
	v_pk_mul_f32 v[112:113], v[112:113], v[112:113]
	v_cvt_pk_bf16_f32 v104, v106, v107
	v_cvt_pk_bf16_f32 v105, v108, v109
	v_pk_mul_f32 v[110:111], v[110:111], v[110:111]
	v_pk_mul_f32 v[116:117], v[116:117], v[116:117]
	v_pk_mul_f32 v[114:115], v[114:115], v[114:115]
	global_store_dwordx4 v[120:121], v[102:105], off
	s_nop 1
	v_cvt_pk_bf16_f32 v102, v110, v111
	v_cvt_pk_bf16_f32 v103, v112, v113
	v_cvt_pk_bf16_f32 v104, v114, v115
	v_cvt_pk_bf16_f32 v105, v116, v117
	global_store_dwordx4 v[122:123], v[102:105], off
	s_nop 1
	v_mov_b32_e32 v106, v243
	s_nop 0
	v_add_u32_e32 v103, 0x80, v168
	v_ashrrev_i32_e32 v102, 8, v103
	v_lshlrev_b32_e32 v107, 7, v103
	v_ashrrev_i32_e32 v103, 31, v102
	v_lshlrev_b64 v[104:105], 7, v[102:103]
	v_lshl_add_u64 v[102:103], v[104:105], 0, s[26:27]
	v_lshl_add_u64 v[104:105], v[104:105], 0, s[28:29]
	v_lshlrev_b64 v[102:103], 15, v[102:103]
	v_lshlrev_b64 v[104:105], 15, v[104:105]
	v_lshl_add_u64 v[102:103], s[12:13], 0, v[102:103]
	v_lshl_add_u64 v[104:105], s[12:13], 0, v[104:105]
	v_and_b32_e32 v138, 0x6780, v107
	v_lshl_add_u64 v[108:109], v[102:103], 0, v[138:139]
	v_lshl_add_u64 v[110:111], v[104:105], 0, v[138:139]
	v_lshl_add_u64 v[108:109], v[108:109], 0, v[90:91]
	v_lshl_add_u64 v[110:111], v[110:111], 0, v[90:91]
	s_nop 0
	v_pk_mul_f32 v[112:113], v[6:7], v[106:107] op_sel_hi:[1,0]
	v_pk_mul_f32 v[114:115], v[8:9], v[106:107] op_sel_hi:[1,0]
	v_pk_mul_f32 v[116:117], v[2:3], v[106:107] op_sel_hi:[1,0]
	v_pk_mul_f32 v[118:119], v[4:5], v[106:107] op_sel_hi:[1,0]
	v_pk_fma_f32 v[84:85], v[114:115], v[84:85], v[28:29]
	v_pk_fma_f32 v[82:83], v[112:113], v[82:83], v[26:27]
	v_pk_mul_f32 v[120:121], v[30:31], v[106:107] op_sel_hi:[1,0]
	v_pk_mul_f32 v[122:123], v[32:33], v[106:107] op_sel_hi:[1,0]
	v_pk_mul_f32 v[124:125], v[14:15], v[106:107] op_sel_hi:[1,0]
	v_pk_mul_f32 v[106:107], v[16:17], v[106:107] op_sel_hi:[1,0]
	v_pk_fma_f32 v[88:89], v[118:119], v[88:89], v[24:25]
	v_pk_fma_f32 v[86:87], v[116:117], v[86:87], v[22:23]
	v_max_f32_e32 v83, 0, v83
	v_max_f32_e32 v82, 0, v82
	v_max_f32_e32 v85, 0, v85
	v_max_f32_e32 v84, 0, v84
	v_pk_fma_f32 v[94:95], v[122:123], v[94:95], v[20:21]
	v_pk_fma_f32 v[92:93], v[120:121], v[92:93], v[18:19]
	v_pk_fma_f32 v[98:99], v[106:107], v[98:99], v[12:13]
	v_pk_fma_f32 v[96:97], v[124:125], v[96:97], v[10:11]
	v_max_f32_e32 v87, 0, v87
	v_max_f32_e32 v86, 0, v86
	v_max_f32_e32 v89, 0, v89
	v_max_f32_e32 v88, 0, v88
	v_pk_mul_f32 v[84:85], v[84:85], v[84:85]
	v_pk_mul_f32 v[82:83], v[82:83], v[82:83]
	v_max_f32_e32 v93, 0, v93
	v_max_f32_e32 v92, 0, v92
	v_max_f32_e32 v95, 0, v95
	v_max_f32_e32 v94, 0, v94
	v_max_f32_e32 v97, 0, v97
	v_max_f32_e32 v96, 0, v96
	v_max_f32_e32 v99, 0, v99
	v_max_f32_e32 v98, 0, v98
	v_pk_mul_f32 v[88:89], v[88:89], v[88:89]
	v_pk_mul_f32 v[86:87], v[86:87], v[86:87]
	v_cvt_pk_bf16_f32 v82, v82, v83
	v_cvt_pk_bf16_f32 v83, v84, v85
	v_pk_mul_f32 v[94:95], v[94:95], v[94:95]
	v_cvt_pk_bf16_f32 v84, v86, v87
	v_cvt_pk_bf16_f32 v85, v88, v89
	v_pk_mul_f32 v[92:93], v[92:93], v[92:93]
	v_pk_mul_f32 v[98:99], v[98:99], v[98:99]
	v_pk_mul_f32 v[96:97], v[96:97], v[96:97]
	global_store_dwordx4 v[108:109], v[82:85], off
	s_nop 1
	v_cvt_pk_bf16_f32 v82, v92, v93
	v_cvt_pk_bf16_f32 v83, v94, v95
	v_cvt_pk_bf16_f32 v84, v96, v97
	v_cvt_pk_bf16_f32 v85, v98, v99
	global_store_dwordx4 v[110:111], v[82:85], off
	s_nop 1
	v_mov_b32_e32 v82, v244
	s_nop 0
	v_add_u32_e32 v83, 0x4800, v169
	v_and_b32_e32 v138, 0x6f80, v83
	v_lshl_add_u64 v[84:85], v[102:103], 0, v[138:139]
	v_lshl_add_u64 v[86:87], v[104:105], 0, v[138:139]
	v_lshl_add_u64 v[84:85], v[84:85], 0, v[90:91]
	v_lshl_add_u64 v[86:87], v[86:87], 0, v[90:91]
	s_nop 0
	v_pk_mul_f32 v[88:89], v[6:7], v[82:83] op_sel_hi:[1,0]
	v_pk_mul_f32 v[92:93], v[8:9], v[82:83] op_sel_hi:[1,0]
	v_pk_mul_f32 v[94:95], v[2:3], v[82:83] op_sel_hi:[1,0]
	v_pk_mul_f32 v[96:97], v[4:5], v[82:83] op_sel_hi:[1,0]
	v_pk_fma_f32 v[68:69], v[92:93], v[68:69], v[28:29]
	v_pk_fma_f32 v[66:67], v[88:89], v[66:67], v[26:27]
	v_pk_mul_f32 v[98:99], v[30:31], v[82:83] op_sel_hi:[1,0]
	v_pk_mul_f32 v[106:107], v[32:33], v[82:83] op_sel_hi:[1,0]
	v_pk_mul_f32 v[108:109], v[14:15], v[82:83] op_sel_hi:[1,0]
	v_pk_mul_f32 v[82:83], v[16:17], v[82:83] op_sel_hi:[1,0]
	v_pk_fma_f32 v[72:73], v[96:97], v[72:73], v[24:25]
	v_pk_fma_f32 v[70:71], v[94:95], v[70:71], v[22:23]
	v_max_f32_e32 v67, 0, v67
	v_max_f32_e32 v66, 0, v66
	v_max_f32_e32 v69, 0, v69
	v_max_f32_e32 v68, 0, v68
	v_pk_fma_f32 v[76:77], v[106:107], v[76:77], v[20:21]
	v_pk_fma_f32 v[74:75], v[98:99], v[74:75], v[18:19]
	v_pk_fma_f32 v[80:81], v[82:83], v[80:81], v[12:13]
	v_pk_fma_f32 v[78:79], v[108:109], v[78:79], v[10:11]
	v_max_f32_e32 v71, 0, v71
	v_max_f32_e32 v70, 0, v70
	v_max_f32_e32 v73, 0, v73
	v_max_f32_e32 v72, 0, v72
	v_pk_mul_f32 v[68:69], v[68:69], v[68:69]
	v_pk_mul_f32 v[66:67], v[66:67], v[66:67]
	v_max_f32_e32 v75, 0, v75
	v_max_f32_e32 v74, 0, v74
	v_max_f32_e32 v77, 0, v77
	v_max_f32_e32 v76, 0, v76
	v_max_f32_e32 v79, 0, v79
	v_max_f32_e32 v78, 0, v78
	v_max_f32_e32 v81, 0, v81
	v_max_f32_e32 v80, 0, v80
	v_pk_mul_f32 v[72:73], v[72:73], v[72:73]
	v_pk_mul_f32 v[70:71], v[70:71], v[70:71]
	v_cvt_pk_bf16_f32 v66, v66, v67
	v_cvt_pk_bf16_f32 v67, v68, v69
	v_pk_mul_f32 v[76:77], v[76:77], v[76:77]
	v_cvt_pk_bf16_f32 v68, v70, v71
	v_cvt_pk_bf16_f32 v69, v72, v73
	v_pk_mul_f32 v[74:75], v[74:75], v[74:75]
	v_pk_mul_f32 v[80:81], v[80:81], v[80:81]
	v_pk_mul_f32 v[78:79], v[78:79], v[78:79]
	global_store_dwordx4 v[84:85], v[66:69], off
	s_nop 1
	v_cvt_pk_bf16_f32 v66, v74, v75
	v_cvt_pk_bf16_f32 v67, v76, v77
	v_cvt_pk_bf16_f32 v68, v78, v79
	v_cvt_pk_bf16_f32 v69, v80, v81
	global_store_dwordx4 v[86:87], v[66:69], off
	s_nop 1
	v_mov_b32_e32 v66, v245
	s_nop 0
	v_add_u32_e32 v67, 0x5000, v169
	v_and_b32_e32 v138, 0x7780, v67
	v_lshl_add_u64 v[68:69], v[102:103], 0, v[138:139]
	v_lshl_add_u64 v[70:71], v[104:105], 0, v[138:139]
	v_lshl_add_u64 v[68:69], v[68:69], 0, v[90:91]
	v_lshl_add_u64 v[70:71], v[70:71], 0, v[90:91]
	s_nop 0
	v_pk_mul_f32 v[72:73], v[6:7], v[66:67] op_sel_hi:[1,0]
	v_pk_mul_f32 v[74:75], v[8:9], v[66:67] op_sel_hi:[1,0]
	v_pk_mul_f32 v[76:77], v[2:3], v[66:67] op_sel_hi:[1,0]
	v_pk_mul_f32 v[78:79], v[4:5], v[66:67] op_sel_hi:[1,0]
	v_pk_fma_f32 v[52:53], v[74:75], v[52:53], v[28:29]
	v_pk_fma_f32 v[50:51], v[72:73], v[50:51], v[26:27]
	v_pk_mul_f32 v[80:81], v[30:31], v[66:67] op_sel_hi:[1,0]
	v_pk_mul_f32 v[82:83], v[32:33], v[66:67] op_sel_hi:[1,0]
	v_pk_mul_f32 v[84:85], v[14:15], v[66:67] op_sel_hi:[1,0]
	v_pk_mul_f32 v[66:67], v[16:17], v[66:67] op_sel_hi:[1,0]
	v_pk_fma_f32 v[56:57], v[78:79], v[56:57], v[24:25]
	v_pk_fma_f32 v[54:55], v[76:77], v[54:55], v[22:23]
	v_max_f32_e32 v51, 0, v51
	v_max_f32_e32 v50, 0, v50
	v_max_f32_e32 v53, 0, v53
	v_max_f32_e32 v52, 0, v52
	v_pk_fma_f32 v[60:61], v[82:83], v[60:61], v[20:21]
	v_pk_fma_f32 v[58:59], v[80:81], v[58:59], v[18:19]
	v_pk_fma_f32 v[64:65], v[66:67], v[64:65], v[12:13]
	v_pk_fma_f32 v[62:63], v[84:85], v[62:63], v[10:11]
	v_max_f32_e32 v55, 0, v55
	v_max_f32_e32 v54, 0, v54
	v_max_f32_e32 v57, 0, v57
	v_max_f32_e32 v56, 0, v56
	v_pk_mul_f32 v[52:53], v[52:53], v[52:53]
	v_pk_mul_f32 v[50:51], v[50:51], v[50:51]
	v_max_f32_e32 v59, 0, v59
	v_max_f32_e32 v58, 0, v58
	v_max_f32_e32 v61, 0, v61
	v_max_f32_e32 v60, 0, v60
	v_max_f32_e32 v63, 0, v63
	v_max_f32_e32 v62, 0, v62
	v_max_f32_e32 v65, 0, v65
	v_max_f32_e32 v64, 0, v64
	v_pk_mul_f32 v[56:57], v[56:57], v[56:57]
	v_pk_mul_f32 v[54:55], v[54:55], v[54:55]
	v_cvt_pk_bf16_f32 v50, v50, v51
	v_cvt_pk_bf16_f32 v51, v52, v53
	v_pk_mul_f32 v[60:61], v[60:61], v[60:61]
	v_cvt_pk_bf16_f32 v52, v54, v55
	v_cvt_pk_bf16_f32 v53, v56, v57
	v_pk_mul_f32 v[58:59], v[58:59], v[58:59]
	v_pk_mul_f32 v[64:65], v[64:65], v[64:65]
	v_pk_mul_f32 v[62:63], v[62:63], v[62:63]
	global_store_dwordx4 v[68:69], v[50:53], off
	s_nop 1
	v_cvt_pk_bf16_f32 v50, v58, v59
	v_cvt_pk_bf16_f32 v51, v60, v61
	v_cvt_pk_bf16_f32 v52, v62, v63
	v_cvt_pk_bf16_f32 v53, v64, v65
	global_store_dwordx4 v[70:71], v[50:53], off
	s_nop 1
	v_mov_b32_e32 v50, v246
	s_nop 0
	v_add_u32_e32 v51, 0x5800, v169
	v_and_b32_e32 v138, 0x7f80, v51
	v_lshl_add_u64 v[52:53], v[102:103], 0, v[138:139]
	v_lshl_add_u64 v[54:55], v[104:105], 0, v[138:139]
	v_lshl_add_u64 v[52:53], v[52:53], 0, v[90:91]
	v_lshl_add_u64 v[54:55], v[54:55], 0, v[90:91]
	s_nop 0
	v_pk_mul_f32 v[2:3], v[2:3], v[50:51] op_sel_hi:[1,0]
	v_pk_mul_f32 v[4:5], v[4:5], v[50:51] op_sel_hi:[1,0]
	v_pk_mul_f32 v[6:7], v[6:7], v[50:51] op_sel_hi:[1,0]
	v_pk_mul_f32 v[8:9], v[8:9], v[50:51] op_sel_hi:[1,0]
	v_pk_mul_f32 v[30:31], v[30:31], v[50:51] op_sel_hi:[1,0]
	v_pk_fma_f32 v[4:5], v[4:5], v[40:41], v[24:25]
	v_pk_fma_f32 v[2:3], v[2:3], v[38:39], v[22:23]
	v_pk_mul_f32 v[32:33], v[32:33], v[50:51] op_sel_hi:[1,0]
	v_pk_mul_f32 v[14:15], v[14:15], v[50:51] op_sel_hi:[1,0]
	v_pk_mul_f32 v[16:17], v[16:17], v[50:51] op_sel_hi:[1,0]
	v_pk_fma_f32 v[8:9], v[8:9], v[36:37], v[28:29]
	v_pk_fma_f32 v[6:7], v[6:7], v[34:35], v[26:27]
	v_pk_fma_f32 v[18:19], v[30:31], v[42:43], v[18:19]
	v_max_f32_e32 v3, 0, v3
	v_max_f32_e32 v2, 0, v2
	v_max_f32_e32 v5, 0, v5
	v_max_f32_e32 v4, 0, v4
	v_pk_fma_f32 v[20:21], v[32:33], v[44:45], v[20:21]
	v_pk_fma_f32 v[12:13], v[16:17], v[48:49], v[12:13]
	v_pk_fma_f32 v[10:11], v[14:15], v[46:47], v[10:11]
	v_max_f32_e32 v7, 0, v7
	v_max_f32_e32 v6, 0, v6
	v_max_f32_e32 v9, 0, v9
	v_max_f32_e32 v8, 0, v8
	v_max_f32_e32 v15, 0, v19
	v_max_f32_e32 v14, 0, v18
	v_pk_mul_f32 v[18:19], v[4:5], v[4:5]
	v_pk_mul_f32 v[4:5], v[2:3], v[2:3]
	v_max_f32_e32 v17, 0, v21
	v_max_f32_e32 v16, 0, v20
	v_max_f32_e32 v11, 0, v11
	v_max_f32_e32 v10, 0, v10
	v_max_f32_e32 v13, 0, v13
	v_max_f32_e32 v12, 0, v12
	v_pk_mul_f32 v[8:9], v[8:9], v[8:9]
	v_pk_mul_f32 v[6:7], v[6:7], v[6:7]
	v_pk_mul_f32 v[16:17], v[16:17], v[16:17]
	v_cvt_pk_bf16_f32 v2, v6, v7
	v_cvt_pk_bf16_f32 v3, v8, v9
	v_cvt_pk_bf16_f32 v4, v4, v5
	v_cvt_pk_bf16_f32 v5, v18, v19
	v_pk_mul_f32 v[14:15], v[14:15], v[14:15]
	v_pk_mul_f32 v[12:13], v[12:13], v[12:13]
	v_pk_mul_f32 v[10:11], v[10:11], v[10:11]
	global_store_dwordx4 v[52:53], v[2:5], off
	s_nop 1
	v_cvt_pk_bf16_f32 v2, v14, v15
	v_cvt_pk_bf16_f32 v3, v16, v17
	v_cvt_pk_bf16_f32 v4, v10, v11
	v_cvt_pk_bf16_f32 v5, v12, v13
	global_store_dwordx4 v[54:55], v[2:5], off
	s_cbranch_vccnz .LBB0_3785
	s_andn2_b64 vcc, exec, s[10:11]
	s_cbranch_vccnz .LBB0_3784
	s_barrier
	s_branch .LBB0_3784
